# LRU: parameter load chain batched (14 steps per wait) on top of W_in round-4/mixer overlap
# speedup vs baseline: 1.0155x; 1.0037x over previous
.LBB0_316:
	v_lshl_add_u64 v[2:3], v[58:59], 0, s[10:11]
	v_mov_b32_e32 v89, v75
	v_lshl_add_u64 v[2:3], v[2:3], 0, v[88:89]
	v_mov_b32_e32 v91, v75
	v_lshl_add_u64 v[52:53], v[2:3], 0, v[90:91]
	v_add_co_u32_e32 v2, vcc, s22, v0
	global_load_dword v16, v[52:53], off offset:256
	global_load_dword v17, v[52:53], off
	global_load_ushort v133, v[0:1], off
	global_load_ushort v134, v[0:1], off offset:3584
	v_addc_co_u32_e32 v3, vcc, 0, v1, vcc
	v_add_co_u32_e32 v4, vcc, s21, v0
	v_mov_b32_e32 v93, v75
	s_nop 0
	v_addc_co_u32_e32 v5, vcc, 0, v1, vcc
	v_add_co_u32_e32 v6, vcc, s23, v0
	v_lshl_add_u64 v[100:101], v[60:61], 0, v[92:93]
	s_nop 0
	v_addc_co_u32_e32 v7, vcc, 0, v1, vcc
	v_add_co_u32_e32 v8, vcc, s26, v0
	s_waitcnt vmcnt(4)
	v_fma_f32 v200, v132, v98, v97
	v_addc_co_u32_e32 v9, vcc, 0, v1, vcc
	v_add_co_u32_e32 v10, vcc, s27, v0
	v_fma_f32 v201, v132, v74, v97
	s_nop 0
	v_addc_co_u32_e32 v11, vcc, 0, v1, vcc
	v_add_co_u32_e32 v12, vcc, s28, v0
	v_fmac_f32_e32 v200, v131, v74
	s_nop 0
	v_addc_co_u32_e32 v13, vcc, 0, v1, vcc
	v_add_co_u32_e32 v14, vcc, s29, v0
	v_fma_f32 v199, v132, v70, v97
	s_nop 0
	v_addc_co_u32_e32 v15, vcc, 0, v1, vcc
	global_load_ushort v142, v[2:3], off offset:3072
	global_load_ushort v139, v[4:5], off offset:2560
	global_load_ushort v138, v[6:7], off offset:2048
	global_load_ushort v135, v[8:9], off offset:1536
	global_load_ushort v136, v[10:11], off offset:1024
	global_load_ushort v137, v[12:13], off offset:512
	global_load_ushort v140, v[14:15], off
	global_load_ushort v141, v[14:15], off offset:3584
	v_add_co_u32_e32 v2, vcc, s30, v0
	v_lshl_add_u64 v[70:71], v[64:65], 0, v[92:93]
	s_nop 0
	v_addc_co_u32_e32 v3, vcc, 0, v1, vcc
	v_add_co_u32_e32 v4, vcc, s31, v0
	v_lshl_add_u64 v[64:65], v[66:67], 0, v[92:93]
	s_nop 0
	v_addc_co_u32_e32 v5, vcc, 0, v1, vcc
	v_add_co_u32_e32 v6, vcc, s34, v0
	v_fmac_f32_e32 v199, v131, v98
	s_nop 0
	v_addc_co_u32_e32 v7, vcc, 0, v1, vcc
	v_add_co_u32_e32 v8, vcc, s35, v0
	v_fmac_f32_e32 v199, v130, v74
	s_nop 0
	v_addc_co_u32_e32 v9, vcc, 0, v1, vcc
	v_add_co_u32_e32 v10, vcc, s36, v0
	s_lshr_b32 s6, s3, 2
	s_nop 0
	v_addc_co_u32_e32 v11, vcc, 0, v1, vcc
	v_add_co_u32_e32 v12, vcc, s37, v0
	s_and_b32 s6, s6, 63
	s_nop 0
	v_addc_co_u32_e32 v13, vcc, 0, v1, vcc
	v_add_co_u32_e32 v14, vcc, s38, v0
	s_lshl_b64 s[96:97], s[18:19], 22
	s_nop 0
	v_addc_co_u32_e32 v15, vcc, 0, v1, vcc
	global_load_ushort v143, v[2:3], off offset:3072
	global_load_ushort v144, v[4:5], off offset:2560
	global_load_ushort v145, v[6:7], off offset:2048
	global_load_ushort v146, v[8:9], off offset:1536
	global_load_ushort v147, v[10:11], off offset:1024
	global_load_ushort v148, v[12:13], off offset:512
	global_load_ushort v149, v[14:15], off
	global_load_ushort v150, v[14:15], off offset:3584
	v_add_co_u32_e32 v2, vcc, s39, v0
	s_lshl_b32 s6, s6, 16
	s_nop 0
	v_addc_co_u32_e32 v3, vcc, 0, v1, vcc
	v_add_co_u32_e32 v4, vcc, s42, v0
	v_lshl_add_u64 v[202:203], v[94:95], 0, v[82:83]
	s_nop 0
	v_addc_co_u32_e32 v5, vcc, 0, v1, vcc
	v_add_co_u32_e32 v6, vcc, s43, v0
	s_or_b32 s96, s96, s6
	s_nop 0
	v_addc_co_u32_e32 v7, vcc, 0, v1, vcc
	v_add_co_u32_e32 v8, vcc, s44, v0
	v_lshl_add_u64 v[98:99], v[202:203], 0, s[96:97]
	s_nop 0
	v_addc_co_u32_e32 v9, vcc, 0, v1, vcc
	v_add_co_u32_e32 v10, vcc, s45, v0
	s_mov_b32 s95, 0
	s_nop 0
	v_addc_co_u32_e32 v11, vcc, 0, v1, vcc
	v_add_co_u32_e32 v12, vcc, s50, v0
	v_mov_b32_e32 v96, 1.0
	s_nop 0
	v_addc_co_u32_e32 v13, vcc, 0, v1, vcc
	v_add_co_u32_e32 v14, vcc, s51, v0
	s_waitcnt vmcnt(15)
	v_lshlrev_b32_e32 v66, 16, v142
	v_addc_co_u32_e32 v15, vcc, 0, v1, vcc
	global_load_ushort v151, v[2:3], off offset:3072
	global_load_ushort v152, v[4:5], off offset:2560
	global_load_ushort v153, v[6:7], off offset:2048
	global_load_ushort v154, v[8:9], off offset:1536
	global_load_ushort v155, v[10:11], off offset:1024
	global_load_ushort v156, v[12:13], off offset:512
	global_load_ushort v157, v[14:15], off
	global_load_ushort v158, v[14:15], off offset:3584
	v_add_co_u32_e32 v2, vcc, s52, v0
	s_waitcnt vmcnt(20)
	v_lshlrev_b32_e32 v74, 16, v135
	v_addc_co_u32_e32 v3, vcc, 0, v1, vcc
	v_add_co_u32_e32 v4, vcc, s53, v0
	s_waitcnt vmcnt(16)
	v_lshlrev_b32_e32 v135, 16, v141
	v_addc_co_u32_e32 v5, vcc, 0, v1, vcc
	v_add_co_u32_e32 v6, vcc, s54, v0
	v_lshlrev_b32_e32 v67, 16, v139
	s_nop 0
	v_addc_co_u32_e32 v7, vcc, 0, v1, vcc
	v_add_co_u32_e32 v8, vcc, s55, v0
	v_lshlrev_b32_e32 v93, 16, v140
	s_nop 0
	v_addc_co_u32_e32 v9, vcc, 0, v1, vcc
	v_add_co_u32_e32 v10, vcc, s56, v0
	v_fma_f32 v202, v132, v135, v97
	s_nop 0
	v_addc_co_u32_e32 v11, vcc, 0, v1, vcc
	v_add_co_u32_e32 v12, vcc, s57, v0
	s_waitcnt vmcnt(12)
	v_lshlrev_b32_e32 v139, 16, v146
	v_addc_co_u32_e32 v13, vcc, 0, v1, vcc
	v_add_co_u32_e32 v14, vcc, s58, v0
	s_waitcnt vmcnt(10)
	v_lshlrev_b32_e32 v141, 16, v148
	v_addc_co_u32_e32 v15, vcc, 0, v1, vcc
	global_load_ushort v159, v[2:3], off offset:3072
	global_load_ushort v160, v[4:5], off offset:2560
	global_load_ushort v161, v[6:7], off offset:2048
	global_load_ushort v162, v[8:9], off offset:1536
	global_load_ushort v163, v[10:11], off offset:1024
	global_load_ushort v164, v[12:13], off offset:512
	global_load_ushort v165, v[14:15], off
	global_load_ushort v166, v[14:15], off offset:3584
	v_add_co_u32_e32 v2, vcc, s59, v0
	s_waitcnt vmcnt(17)
	v_lshlrev_b32_e32 v142, 16, v149
	v_addc_co_u32_e32 v3, vcc, 0, v1, vcc
	v_add_co_u32_e32 v4, vcc, s60, v0
	v_lshlrev_b32_e32 v140, 16, v147
	s_nop 0
	v_addc_co_u32_e32 v5, vcc, 0, v1, vcc
	v_add_co_u32_e32 v6, vcc, s61, v0
	v_fma_f32 v206, v132, v139, v97
	s_nop 0
	v_addc_co_u32_e32 v7, vcc, 0, v1, vcc
	v_add_co_u32_e32 v8, vcc, s62, v0
	v_fma_f32 v207, v132, v140, v97
	s_nop 0
	v_addc_co_u32_e32 v9, vcc, 0, v1, vcc
	v_add_co_u32_e32 v10, vcc, s63, v0
	v_fma_f32 v208, v132, v141, v97
	s_nop 0
	v_addc_co_u32_e32 v11, vcc, 0, v1, vcc
	v_add_co_u32_e32 v12, vcc, s64, v0
	v_fma_f32 v209, v132, v142, v97
	s_nop 0
	v_addc_co_u32_e32 v13, vcc, 0, v1, vcc
	v_add_co_u32_e32 v14, vcc, s65, v0
	s_waitcnt vmcnt(11)
	v_lshlrev_b32_e32 v148, 16, v155
	v_addc_co_u32_e32 v15, vcc, 0, v1, vcc
	global_load_ushort v167, v[2:3], off offset:3072
	global_load_ushort v168, v[4:5], off offset:2560
	global_load_ushort v169, v[6:7], off offset:2048
	global_load_ushort v170, v[8:9], off offset:1536
	global_load_ushort v171, v[10:11], off offset:1024
	global_load_ushort v172, v[12:13], off offset:512
	global_load_ushort v173, v[14:15], off
	global_load_ushort v174, v[14:15], off offset:3584
	v_add_co_u32_e32 v2, vcc, s66, v0
	s_waitcnt vmcnt(18)
	v_lshlrev_b32_e32 v149, 16, v156
	v_addc_co_u32_e32 v3, vcc, 0, v1, vcc
	v_add_co_u32_e32 v4, vcc, s67, v0
	v_lshlrev_b32_e32 v146, 16, v153
	s_nop 0
	v_addc_co_u32_e32 v5, vcc, 0, v1, vcc
	v_add_co_u32_e32 v6, vcc, s70, v0
	v_lshlrev_b32_e32 v147, 16, v154
	s_nop 0
	v_addc_co_u32_e32 v7, vcc, 0, v1, vcc
	v_add_co_u32_e32 v8, vcc, s71, v0
	v_fma_f32 v213, v132, v146, v97
	s_nop 0
	v_addc_co_u32_e32 v9, vcc, 0, v1, vcc
	v_add_co_u32_e32 v10, vcc, s72, v0
	v_fma_f32 v214, v132, v147, v97
	s_nop 0
	v_addc_co_u32_e32 v11, vcc, 0, v1, vcc
	v_add_co_u32_e32 v12, vcc, s73, v0
	v_fma_f32 v215, v132, v148, v97
	s_nop 0
	v_addc_co_u32_e32 v13, vcc, 0, v1, vcc
	v_add_co_u32_e32 v14, vcc, s74, v0
	v_fma_f32 v216, v132, v149, v97
	s_nop 0
	v_addc_co_u32_e32 v15, vcc, 0, v1, vcc
	global_load_ushort v175, v[2:3], off offset:3072
	global_load_ushort v178, v[4:5], off offset:2560
	global_load_ushort v179, v[6:7], off offset:2048
	global_load_ushort v180, v[8:9], off offset:1536
	global_load_ushort v181, v[10:11], off offset:1024
	global_load_ushort v182, v[12:13], off offset:512
	global_load_ushort v183, v[14:15], off
	global_load_ushort v184, v[14:15], off offset:3584
	v_add_co_u32_e32 v2, vcc, s75, v0
	s_waitcnt vmcnt(22)
	v_lshlrev_b32_e32 v153, 16, v160
	v_addc_co_u32_e32 v3, vcc, 0, v1, vcc
	v_add_co_u32_e32 v4, vcc, s76, v0
	s_waitcnt vmcnt(20)
	v_lshlrev_b32_e32 v155, 16, v162
	v_addc_co_u32_e32 v5, vcc, 0, v1, vcc
	v_add_co_u32_e32 v6, vcc, s77, v0
	s_waitcnt vmcnt(19)
	v_lshlrev_b32_e32 v156, 16, v163
	v_addc_co_u32_e32 v7, vcc, 0, v1, vcc
	v_add_co_u32_e32 v8, vcc, s78, v0
	v_lshlrev_b32_e32 v154, 16, v161
	s_nop 0
	v_addc_co_u32_e32 v9, vcc, 0, v1, vcc
	v_add_co_u32_e32 v10, vcc, s79, v0
	v_fma_f32 v220, v132, v153, v97
	s_nop 0
	v_addc_co_u32_e32 v11, vcc, 0, v1, vcc
	v_add_co_u32_e32 v12, vcc, s80, v0
	v_fma_f32 v221, v132, v154, v97
	s_nop 0
	v_addc_co_u32_e32 v13, vcc, 0, v1, vcc
	v_add_co_u32_e32 v14, vcc, s81, v0
	v_fma_f32 v222, v132, v155, v97
	s_nop 0
	v_addc_co_u32_e32 v15, vcc, 0, v1, vcc
	global_load_ushort v185, v[2:3], off offset:3072
	global_load_ushort v186, v[4:5], off offset:2560
	global_load_ushort v187, v[6:7], off offset:2048
	global_load_ushort v188, v[8:9], off offset:1536
	global_load_ushort v189, v[10:11], off offset:1024
	global_load_ushort v190, v[12:13], off offset:512
	global_load_ushort v191, v[14:15], off
	global_load_ushort v192, v[14:15], off offset:3584
	v_add_co_u32_e32 v2, vcc, s82, v0
	s_waitcnt vmcnt(21)
	v_lshlrev_b32_e32 v162, 16, v169
	v_addc_co_u32_e32 v3, vcc, 0, v1, vcc
	v_add_co_u32_e32 v4, vcc, s83, v0
	s_waitcnt vmcnt(20)
	v_lshlrev_b32_e32 v163, 16, v170
	v_addc_co_u32_e32 v5, vcc, 0, v1, vcc
	v_add_co_u32_e32 v6, vcc, s84, v0
	v_lshlrev_b32_e32 v160, 16, v167
	s_nop 0
	v_addc_co_u32_e32 v7, vcc, 0, v1, vcc
	v_add_co_u32_e32 v8, vcc, s85, v0
	v_lshlrev_b32_e32 v161, 16, v168
	s_nop 0
	v_addc_co_u32_e32 v9, vcc, 0, v1, vcc
	v_add_co_u32_e32 v10, vcc, s86, v0
	s_waitcnt vmcnt(16)
	v_lshlrev_b32_e32 v167, 16, v174
	v_addc_co_u32_e32 v11, vcc, 0, v1, vcc
	v_add_co_u32_e32 v0, vcc, s87, v0
	v_fma_f32 v223, v132, v156, v97
	s_nop 0
	v_addc_co_u32_e32 v1, vcc, 0, v1, vcc
	global_load_ushort v193, v[2:3], off offset:3072
	global_load_ushort v194, v[4:5], off offset:2560
	global_load_ushort v195, v[6:7], off offset:2048
	global_load_ushort v196, v[8:9], off offset:1536
	global_load_ushort v197, v[10:11], off offset:1024
	global_load_ushort v198, v[0:1], off offset:512
	v_cvt_pk_bf16_f32 v0, v17, v16
	global_load_dword v1, v[52:53], off offset:768
	global_load_dword v2, v[52:53], off offset:512
	s_waitcnt vmcnt(0)
	v_cvt_pk_bf16_f32 v1, v2, v1
	global_load_dword v226, v[52:53], off offset:1280
	global_load_dword v227, v[52:53], off offset:1024
	global_load_dword v228, v[52:53], off offset:1792
	global_load_dword v229, v[52:53], off offset:1536
	v_lshl_add_u64 v[4:5], v[62:63], 0, s[10:11]
	v_lshl_add_u64 v[4:5], v[4:5], 0, v[88:89]
	v_lshl_add_u64 v[56:57], v[4:5], 0, v[90:91]
	global_load_dword v230, v[56:57], off offset:256
	global_load_dword v231, v[56:57], off
	global_load_dword v232, v[56:57], off offset:768
	global_load_dword v233, v[56:57], off offset:512
	global_load_dword v234, v[56:57], off offset:1280
	global_load_dword v235, v[56:57], off offset:1024
	global_load_dword v236, v[56:57], off offset:1792
	global_load_dword v237, v[56:57], off offset:1536
	v_add_co_u32_e32 v62, vcc, s21, v52
	s_nop 0
	v_addc_co_u32_e32 v63, vcc, 0, v53, vcc
	global_load_dword v238, v[62:63], off offset:256
	global_load_dword v239, v[62:63], off
	global_load_dword v240, v[62:63], off offset:768
	global_load_dword v241, v[62:63], off offset:512
	global_load_dword v242, v[62:63], off offset:1280
	global_load_dword v243, v[62:63], off offset:1024
	global_load_dword v244, v[62:63], off offset:1792
	global_load_dword v245, v[62:63], off offset:1536
	v_add_co_u32_e32 v68, vcc, s21, v56
	s_nop 0
	v_addc_co_u32_e32 v69, vcc, 0, v57, vcc
	global_load_dword v246, v[68:69], off offset:256
	global_load_dword v247, v[68:69], off
	global_load_dword v248, v[68:69], off offset:768
	global_load_dword v249, v[68:69], off offset:512
	global_load_dword v250, v[68:69], off offset:1280
	global_load_dword v251, v[68:69], off offset:1024
	global_load_dword v252, v[68:69], off offset:1792
	global_load_dword v253, v[68:69], off offset:1536
	s_waitcnt vmcnt(0)
	v_cvt_pk_bf16_f32 v2, v227, v226
	v_cvt_pk_bf16_f32 v3, v229, v228
	v_cvt_pk_bf16_f32 v4, v231, v230
	v_cvt_pk_bf16_f32 v5, v233, v232
	v_cvt_pk_bf16_f32 v6, v235, v234
	v_cvt_pk_bf16_f32 v7, v237, v236
	v_cvt_pk_bf16_f32 v8, v239, v238
	v_cvt_pk_bf16_f32 v9, v241, v240
	v_cvt_pk_bf16_f32 v10, v243, v242
	v_cvt_pk_bf16_f32 v11, v245, v244
	v_cvt_pk_bf16_f32 v12, v247, v246
	v_cvt_pk_bf16_f32 v13, v249, v248
	v_cvt_pk_bf16_f32 v14, v251, v250
	v_cvt_pk_bf16_f32 v15, v253, v252
	global_load_dword v226, v[52:53], off offset:320
	global_load_dword v227, v[52:53], off offset:64
	global_load_dword v228, v[52:53], off offset:832
	global_load_dword v229, v[52:53], off offset:576
	global_load_dword v230, v[52:53], off offset:1344
	global_load_dword v231, v[52:53], off offset:1088
	global_load_dword v232, v[52:53], off offset:1856
	global_load_dword v233, v[52:53], off offset:1600
	global_load_dword v234, v[56:57], off offset:320
	global_load_dword v235, v[56:57], off offset:64
	global_load_dword v236, v[56:57], off offset:832
	global_load_dword v237, v[56:57], off offset:576
	global_load_dword v238, v[56:57], off offset:1344
	global_load_dword v239, v[56:57], off offset:1088
	global_load_dword v240, v[56:57], off offset:1856
	global_load_dword v241, v[56:57], off offset:1600
	global_load_dword v242, v[62:63], off offset:320
	global_load_dword v243, v[62:63], off offset:64
	global_load_dword v244, v[62:63], off offset:832
	global_load_dword v245, v[62:63], off offset:576
	global_load_dword v246, v[62:63], off offset:1344
	global_load_dword v247, v[62:63], off offset:1088
	global_load_dword v248, v[62:63], off offset:1856
	global_load_dword v249, v[62:63], off offset:1600
	global_load_dword v250, v[68:69], off offset:320
	global_load_dword v251, v[68:69], off offset:64
	global_load_dword v252, v[68:69], off offset:832
	global_load_dword v253, v[68:69], off offset:576
	s_waitcnt vmcnt(0)
	v_cvt_pk_bf16_f32 v16, v227, v226
	v_cvt_pk_bf16_f32 v17, v229, v228
	v_cvt_pk_bf16_f32 v18, v231, v230
	v_cvt_pk_bf16_f32 v19, v233, v232
	v_cvt_pk_bf16_f32 v20, v235, v234
	v_cvt_pk_bf16_f32 v21, v237, v236
	v_cvt_pk_bf16_f32 v22, v239, v238
	v_cvt_pk_bf16_f32 v23, v241, v240
	v_cvt_pk_bf16_f32 v24, v243, v242
	v_cvt_pk_bf16_f32 v25, v245, v244
	v_cvt_pk_bf16_f32 v26, v247, v246
	v_cvt_pk_bf16_f32 v27, v249, v248
	v_cvt_pk_bf16_f32 v28, v251, v250
	v_cvt_pk_bf16_f32 v29, v253, v252
	global_load_dword v226, v[68:69], off offset:1344
	global_load_dword v227, v[68:69], off offset:1088
	global_load_dword v228, v[68:69], off offset:1856
	global_load_dword v229, v[68:69], off offset:1600
	global_load_dword v230, v[52:53], off offset:384
	global_load_dword v231, v[52:53], off offset:128
	global_load_dword v232, v[52:53], off offset:896
	global_load_dword v233, v[52:53], off offset:640
	global_load_dword v234, v[52:53], off offset:1408
	global_load_dword v235, v[52:53], off offset:1152
	global_load_dword v236, v[52:53], off offset:1920
	global_load_dword v237, v[52:53], off offset:1664
	global_load_dword v238, v[56:57], off offset:384
	global_load_dword v239, v[56:57], off offset:128
	global_load_dword v240, v[56:57], off offset:896
	global_load_dword v241, v[56:57], off offset:640
	global_load_dword v242, v[56:57], off offset:1408
	global_load_dword v243, v[56:57], off offset:1152
	global_load_dword v244, v[56:57], off offset:1920
	global_load_dword v245, v[56:57], off offset:1664
	global_load_dword v246, v[62:63], off offset:384
	global_load_dword v247, v[62:63], off offset:128
	global_load_dword v248, v[62:63], off offset:896
	global_load_dword v249, v[62:63], off offset:640
	global_load_dword v250, v[62:63], off offset:1408
	global_load_dword v251, v[62:63], off offset:1152
	global_load_dword v252, v[62:63], off offset:1920
	global_load_dword v253, v[62:63], off offset:1664
	s_waitcnt vmcnt(0)
	v_cvt_pk_bf16_f32 v30, v227, v226
	v_cvt_pk_bf16_f32 v31, v229, v228
	v_cvt_pk_bf16_f32 v32, v231, v230
	v_cvt_pk_bf16_f32 v33, v233, v232
	v_cvt_pk_bf16_f32 v34, v235, v234
	v_cvt_pk_bf16_f32 v35, v237, v236
	v_cvt_pk_bf16_f32 v36, v239, v238
	v_cvt_pk_bf16_f32 v37, v241, v240
	v_cvt_pk_bf16_f32 v38, v243, v242
	v_cvt_pk_bf16_f32 v39, v245, v244
	v_cvt_pk_bf16_f32 v40, v247, v246
	v_cvt_pk_bf16_f32 v41, v249, v248
	v_cvt_pk_bf16_f32 v42, v251, v250
	v_cvt_pk_bf16_f32 v43, v253, v252
	global_load_dword v226, v[68:69], off offset:384
	global_load_dword v227, v[68:69], off offset:128
	global_load_dword v228, v[68:69], off offset:896
	global_load_dword v229, v[68:69], off offset:640
	global_load_dword v230, v[68:69], off offset:1408
	global_load_dword v231, v[68:69], off offset:1152
	global_load_dword v232, v[68:69], off offset:1920
	global_load_dword v233, v[68:69], off offset:1664
	global_load_dword v234, v[52:53], off offset:448
	global_load_dword v235, v[52:53], off offset:192
	global_load_dword v236, v[52:53], off offset:960
	global_load_dword v237, v[52:53], off offset:704
	global_load_dword v238, v[52:53], off offset:1472
	global_load_dword v239, v[52:53], off offset:1216
	global_load_dword v240, v[52:53], off offset:1984
	s_nop 0
	global_load_dword v241, v[52:53], off offset:1728
	global_load_dword v242, v[56:57], off offset:448
	global_load_dword v243, v[56:57], off offset:192
	global_load_dword v244, v[56:57], off offset:960
	global_load_dword v245, v[56:57], off offset:704
	global_load_dword v246, v[56:57], off offset:1472
	global_load_dword v247, v[56:57], off offset:1216
	global_load_dword v248, v[56:57], off offset:1984
	s_nop 0
	global_load_dword v249, v[56:57], off offset:1728
	global_load_dword v250, v[62:63], off offset:448
	global_load_dword v251, v[62:63], off offset:192
	global_load_dword v252, v[62:63], off offset:960
	global_load_dword v253, v[62:63], off offset:704
	s_waitcnt vmcnt(0)
	v_cvt_pk_bf16_f32 v44, v227, v226
	v_cvt_pk_bf16_f32 v45, v229, v228
	v_cvt_pk_bf16_f32 v46, v231, v230
	v_cvt_pk_bf16_f32 v47, v233, v232
	v_cvt_pk_bf16_f32 v48, v235, v234
	v_cvt_pk_bf16_f32 v49, v237, v236
	v_cvt_pk_bf16_f32 v50, v239, v238
	v_cvt_pk_bf16_f32 v51, v241, v240
	v_cvt_pk_bf16_f32 v52, v243, v242
	v_cvt_pk_bf16_f32 v53, v245, v244
	v_cvt_pk_bf16_f32 v54, v247, v246
	v_cvt_pk_bf16_f32 v55, v249, v248
	v_cvt_pk_bf16_f32 v56, v251, v250
	v_cvt_pk_bf16_f32 v57, v253, v252
	global_load_dword v226, v[62:63], off offset:1472
	global_load_dword v227, v[62:63], off offset:1216
	global_load_dword v228, v[62:63], off offset:1984
	s_nop 0
	global_load_dword v229, v[62:63], off offset:1728
	global_load_dword v230, v[68:69], off offset:448
	global_load_dword v231, v[68:69], off offset:192
	v_lshlrev_b32_e32 v62, 16, v133
	v_lshlrev_b32_e32 v63, 16, v134
	v_fmac_f32_e32 v200, v130, v62
	v_fmac_f32_e32 v201, v131, v62
	v_fma_f32 v133, v132, v62, v97
	v_fma_f32 v134, v132, v63, v97
	v_fmac_f32_e32 v200, v129, v63
	v_fmac_f32_e32 v201, v130, v63
	v_fmac_f32_e32 v133, v131, v63
	global_load_dword v232, v[68:69], off offset:960
	global_load_dword v233, v[68:69], off offset:704
	v_lshlrev_b32_e32 v169, 16, v178
	v_lshlrev_b32_e32 v178, 16, v185
	v_lshlrev_b32_e32 v185, 16, v192
	v_fmac_f32_e32 v134, v131, v66
	v_fma_f32 v192, v132, v66, v97
	v_fmac_f32_e32 v201, v129, v66
	v_fmac_f32_e32 v133, v130, v66
	s_waitcnt vmcnt(0)
	v_cvt_pk_bf16_f32 v58, v227, v226
	v_cvt_pk_bf16_f32 v59, v229, v228
	v_cvt_pk_bf16_f32 v60, v231, v230
	v_cvt_pk_bf16_f32 v61, v233, v232
	global_load_dword v63, v[68:69], off offset:1472
	global_load_dword v66, v[68:69], off offset:1216
	v_fmac_f32_e32 v199, v129, v62
	v_lshlrev_b32_e32 v62, 16, v138
	v_lshlrev_b32_e32 v170, 16, v179
	v_lshlrev_b32_e32 v179, 16, v186
	v_lshlrev_b32_e32 v186, 16, v193
	v_fma_f32 v193, v132, v67, v97
	v_fmac_f32_e32 v134, v130, v67
	v_fmac_f32_e32 v192, v131, v67
	v_lshlrev_b32_e32 v89, 16, v136
	v_lshlrev_b32_e32 v136, 16, v143
	v_lshlrev_b32_e32 v143, 16, v150
	v_lshlrev_b32_e32 v150, 16, v157
	v_lshlrev_b32_e32 v157, 16, v164
	v_lshlrev_b32_e32 v164, 16, v171
	v_lshlrev_b32_e32 v171, 16, v180
	v_lshlrev_b32_e32 v180, 16, v187
	v_lshlrev_b32_e32 v187, 16, v194
	v_fma_f32 v194, v132, v62, v97
	v_fmac_f32_e32 v193, v131, v62
	v_fmac_f32_e32 v134, v129, v62
	v_fmac_f32_e32 v192, v130, v62
	s_waitcnt vmcnt(0)
	v_cvt_pk_bf16_f32 v62, v66, v63
	global_load_dword v63, v[68:69], off offset:1984
	global_load_dword v66, v[68:69], off offset:1728
	v_lshlrev_b32_e32 v91, 16, v137
	v_lshlrev_b32_e32 v137, 16, v144
	v_lshlrev_b32_e32 v138, 16, v145
	v_lshlrev_b32_e32 v144, 16, v151
	v_lshlrev_b32_e32 v145, 16, v152
	v_lshlrev_b32_e32 v151, 16, v158
	v_lshlrev_b32_e32 v152, 16, v159
	v_lshlrev_b32_e32 v158, 16, v165
	v_lshlrev_b32_e32 v159, 16, v166
	v_lshlrev_b32_e32 v165, 16, v172
	v_lshlrev_b32_e32 v166, 16, v173
	v_lshlrev_b32_e32 v168, 16, v175
	v_lshlrev_b32_e32 v172, 16, v181
	v_lshlrev_b32_e32 v173, 16, v182
	v_lshlrev_b32_e32 v174, 16, v183
	v_lshlrev_b32_e32 v175, 16, v184
	v_lshlrev_b32_e32 v181, 16, v188
	v_lshlrev_b32_e32 v182, 16, v189
	v_lshlrev_b32_e32 v183, 16, v190
	v_lshlrev_b32_e32 v184, 16, v191
	v_lshlrev_b32_e32 v188, 16, v195
	v_lshlrev_b32_e32 v189, 16, v196
	v_lshlrev_b32_e32 v190, 16, v197
	v_lshlrev_b32_e32 v191, 16, v198
	v_fma_f32 v195, v132, v74, v97
	v_fma_f32 v196, v132, v89, v97
	v_fma_f32 v197, v132, v91, v97
	v_fma_f32 v198, v132, v93, v97
	v_fma_f32 v203, v132, v136, v97
	v_fma_f32 v204, v132, v137, v97
	v_fma_f32 v205, v132, v138, v97
	v_fma_f32 v210, v132, v143, v97
	v_fma_f32 v211, v132, v144, v97
	v_fma_f32 v212, v132, v145, v97
	v_fma_f32 v217, v132, v150, v97
	v_fma_f32 v218, v132, v151, v97
	v_fma_f32 v219, v132, v152, v97
	v_fma_f32 v224, v132, v157, v97
	v_fma_f32 v225, v132, v158, v97
	v_fma_f32 v226, v132, v159, v97
	v_fma_f32 v227, v132, v160, v97
	v_fma_f32 v228, v132, v161, v97
	v_fma_f32 v229, v132, v162, v97
	v_fma_f32 v230, v132, v163, v97
	v_fma_f32 v231, v132, v164, v97
	v_fma_f32 v232, v132, v165, v97
	v_fma_f32 v233, v132, v166, v97
	v_fma_f32 v234, v132, v167, v97
	v_fma_f32 v235, v132, v168, v97
	v_fma_f32 v236, v132, v169, v97
	v_fma_f32 v237, v132, v170, v97
	v_fma_f32 v238, v132, v171, v97
	v_fma_f32 v239, v132, v172, v97
	v_fma_f32 v240, v132, v173, v97
	v_fma_f32 v241, v132, v174, v97
	v_fma_f32 v242, v132, v175, v97
	v_fma_f32 v243, v132, v178, v97
	v_fma_f32 v244, v132, v179, v97
	v_fma_f32 v245, v132, v180, v97
	v_fma_f32 v246, v132, v181, v97
	v_fma_f32 v247, v132, v182, v97
	v_fma_f32 v248, v132, v183, v97
	v_fma_f32 v249, v132, v184, v97
	v_fma_f32 v250, v132, v185, v97
	v_fma_f32 v251, v132, v186, v97
	v_fma_f32 v252, v132, v187, v97
	v_fmac_f32_e32 v97, v132, v188
	v_fmac_f32_e32 v194, v131, v74
	v_fmac_f32_e32 v195, v131, v89
	v_fmac_f32_e32 v196, v131, v91
	v_fmac_f32_e32 v197, v131, v93
	v_fmac_f32_e32 v198, v131, v135
	v_fmac_f32_e32 v202, v131, v136
	v_fmac_f32_e32 v203, v131, v137
	v_fmac_f32_e32 v204, v131, v138
	v_fmac_f32_e32 v205, v131, v139
	v_fmac_f32_e32 v206, v131, v140
	v_fmac_f32_e32 v207, v131, v141
	v_fmac_f32_e32 v208, v131, v142
	v_fmac_f32_e32 v209, v131, v143
	v_fmac_f32_e32 v210, v131, v144
	v_fmac_f32_e32 v211, v131, v145
	v_fmac_f32_e32 v212, v131, v146
	v_fmac_f32_e32 v213, v131, v147
	v_fmac_f32_e32 v214, v131, v148
	v_fmac_f32_e32 v215, v131, v149
	v_fmac_f32_e32 v216, v131, v150
	v_fmac_f32_e32 v217, v131, v151
	v_fmac_f32_e32 v218, v131, v152
	v_fmac_f32_e32 v219, v131, v153
	v_fmac_f32_e32 v220, v131, v154
	v_fmac_f32_e32 v221, v131, v155
	v_fmac_f32_e32 v222, v131, v156
	v_fmac_f32_e32 v223, v131, v157
	v_fmac_f32_e32 v224, v131, v158
	v_fmac_f32_e32 v225, v131, v159
	v_fmac_f32_e32 v226, v131, v160
	v_fmac_f32_e32 v227, v131, v161
	v_fmac_f32_e32 v228, v131, v162
	v_fmac_f32_e32 v229, v131, v163
	v_fmac_f32_e32 v230, v131, v164
	v_fmac_f32_e32 v231, v131, v165
	v_fmac_f32_e32 v232, v131, v166
	v_fmac_f32_e32 v233, v131, v167
	v_fmac_f32_e32 v234, v131, v168
	v_fmac_f32_e32 v235, v131, v169
	v_fmac_f32_e32 v236, v131, v170
	v_fmac_f32_e32 v237, v131, v171
	v_fmac_f32_e32 v238, v131, v172
	v_fmac_f32_e32 v239, v131, v173
	v_fmac_f32_e32 v240, v131, v174
	v_fmac_f32_e32 v241, v131, v175
	v_fmac_f32_e32 v242, v131, v178
	v_fmac_f32_e32 v243, v131, v179
	v_fmac_f32_e32 v244, v131, v180
	v_fmac_f32_e32 v245, v131, v181
	v_fmac_f32_e32 v246, v131, v182
	v_fmac_f32_e32 v247, v131, v183
	v_fmac_f32_e32 v248, v131, v184
	v_fmac_f32_e32 v249, v131, v185
	v_fmac_f32_e32 v250, v131, v186
	v_fmac_f32_e32 v251, v131, v187
	v_fmac_f32_e32 v252, v131, v188
	v_fmac_f32_e32 v97, v131, v189
	v_fmac_f32_e32 v193, v130, v74
	v_fmac_f32_e32 v194, v130, v89
	v_fmac_f32_e32 v195, v130, v91
	v_fmac_f32_e32 v196, v130, v93
	v_fmac_f32_e32 v197, v130, v135
	v_fmac_f32_e32 v198, v130, v136
	v_fmac_f32_e32 v202, v130, v137
	v_fmac_f32_e32 v203, v130, v138
	v_fmac_f32_e32 v204, v130, v139
	v_fmac_f32_e32 v205, v130, v140
	v_fmac_f32_e32 v206, v130, v141
	v_fmac_f32_e32 v207, v130, v142
	v_fmac_f32_e32 v208, v130, v143
	v_fmac_f32_e32 v209, v130, v144
	v_fmac_f32_e32 v210, v130, v145
	v_fmac_f32_e32 v211, v130, v146
	v_fmac_f32_e32 v212, v130, v147
	v_fmac_f32_e32 v213, v130, v148
	v_fmac_f32_e32 v214, v130, v149
	v_fmac_f32_e32 v215, v130, v150
	v_fmac_f32_e32 v216, v130, v151
	v_fmac_f32_e32 v217, v130, v152
	v_fmac_f32_e32 v218, v130, v153
	v_fmac_f32_e32 v219, v130, v154
	v_fmac_f32_e32 v220, v130, v155
	v_fmac_f32_e32 v221, v130, v156
	v_fmac_f32_e32 v222, v130, v157
	v_fmac_f32_e32 v223, v130, v158
	v_fmac_f32_e32 v224, v130, v159
	v_fmac_f32_e32 v225, v130, v160
	v_fmac_f32_e32 v226, v130, v161
	v_fmac_f32_e32 v227, v130, v162
	v_fmac_f32_e32 v228, v130, v163
	v_fmac_f32_e32 v229, v130, v164
	v_fmac_f32_e32 v230, v130, v165
	v_fmac_f32_e32 v231, v130, v166
	v_fmac_f32_e32 v232, v130, v167
	v_fmac_f32_e32 v233, v130, v168
	v_fmac_f32_e32 v234, v130, v169
	v_fmac_f32_e32 v235, v130, v170
	v_fmac_f32_e32 v236, v130, v171
	v_fmac_f32_e32 v237, v130, v172
	v_fmac_f32_e32 v238, v130, v173
	v_fmac_f32_e32 v239, v130, v174
	v_fmac_f32_e32 v240, v130, v175
	v_fmac_f32_e32 v241, v130, v178
	v_fmac_f32_e32 v242, v130, v179
	v_fmac_f32_e32 v243, v130, v180
	v_fmac_f32_e32 v244, v130, v181
	v_fmac_f32_e32 v245, v130, v182
	v_fmac_f32_e32 v246, v130, v183
	v_fmac_f32_e32 v247, v130, v184
	v_fmac_f32_e32 v248, v130, v185
	v_fmac_f32_e32 v249, v130, v186
	v_fmac_f32_e32 v250, v130, v187
	v_fmac_f32_e32 v251, v130, v188
	v_fmac_f32_e32 v252, v130, v189
	v_fmac_f32_e32 v97, v130, v190
	v_fmac_f32_e32 v133, v129, v67
	v_fmac_f32_e32 v192, v129, v74
	v_fmac_f32_e32 v193, v129, v89
	v_fmac_f32_e32 v194, v129, v91
	v_fmac_f32_e32 v195, v129, v93
	v_fmac_f32_e32 v196, v129, v135
	v_fmac_f32_e32 v197, v129, v136
	v_fmac_f32_e32 v198, v129, v137
	v_fmac_f32_e32 v202, v129, v138
	v_fmac_f32_e32 v203, v129, v139
	v_fmac_f32_e32 v204, v129, v140
	v_fmac_f32_e32 v205, v129, v141
	v_fmac_f32_e32 v206, v129, v142
	v_fmac_f32_e32 v207, v129, v143
	v_fmac_f32_e32 v208, v129, v144
	v_fmac_f32_e32 v209, v129, v145
	v_fmac_f32_e32 v210, v129, v146
	v_fmac_f32_e32 v211, v129, v147
	v_fmac_f32_e32 v212, v129, v148
	v_fmac_f32_e32 v213, v129, v149
	v_fmac_f32_e32 v214, v129, v150
	v_fmac_f32_e32 v215, v129, v151
	v_fmac_f32_e32 v216, v129, v152
	v_fmac_f32_e32 v217, v129, v153
	v_fmac_f32_e32 v218, v129, v154
	v_fmac_f32_e32 v219, v129, v155
	v_fmac_f32_e32 v220, v129, v156
	v_fmac_f32_e32 v221, v129, v157
	v_fmac_f32_e32 v222, v129, v158
	v_fmac_f32_e32 v223, v129, v159
	v_fmac_f32_e32 v224, v129, v160
	v_fmac_f32_e32 v225, v129, v161
	v_fmac_f32_e32 v226, v129, v162
	v_fmac_f32_e32 v227, v129, v163
	v_fmac_f32_e32 v228, v129, v164
	v_fmac_f32_e32 v229, v129, v165
	v_fmac_f32_e32 v230, v129, v166
	v_fmac_f32_e32 v231, v129, v167
	v_fmac_f32_e32 v232, v129, v168
	v_fmac_f32_e32 v233, v129, v169
	v_fmac_f32_e32 v234, v129, v170
	v_fmac_f32_e32 v235, v129, v171
	v_fmac_f32_e32 v236, v129, v172
	v_fmac_f32_e32 v237, v129, v173
	v_fmac_f32_e32 v238, v129, v174
	v_fmac_f32_e32 v239, v129, v175
	v_fmac_f32_e32 v240, v129, v178
	v_fmac_f32_e32 v241, v129, v179
	v_fmac_f32_e32 v242, v129, v180
	v_fmac_f32_e32 v243, v129, v181
	v_fmac_f32_e32 v244, v129, v182
	v_fmac_f32_e32 v245, v129, v183
	v_fmac_f32_e32 v246, v129, v184
	v_fmac_f32_e32 v247, v129, v185
	v_fmac_f32_e32 v248, v129, v186
	v_fmac_f32_e32 v249, v129, v187
	v_fmac_f32_e32 v250, v129, v188
	v_fmac_f32_e32 v251, v129, v189
	v_fmac_f32_e32 v252, v129, v190
	v_fmac_f32_e32 v97, v129, v191
	s_waitcnt vmcnt(0)
	v_cvt_pk_bf16_f32 v63, v66, v63
	global_load_dword v74, v[100:101], off
	global_load_dword v89, v[100:101], off offset:64
	global_load_dword v91, v[100:101], off offset:128
	global_load_dword v93, v[100:101], off offset:192
	global_load_dword v129, v[70:71], off
	global_load_dword v130, v[70:71], off offset:64
	global_load_dword v131, v[70:71], off offset:128
	global_load_dword v132, v[70:71], off offset:192
	global_load_dword v66, v[64:65], off
	global_load_dword v67, v[64:65], off offset:64
	global_load_dword v68, v[64:65], off offset:128
	s_nop 0
	global_load_dword v64, v[64:65], off offset:192
	v_cvt_pk_bf16_f32 v65, v199, v199
	ds_write_b16 v73, v65
	v_cvt_pk_bf16_f32 v65, v200, v200
	ds_write_b16 v73, v65 offset:144
	v_cvt_pk_bf16_f32 v65, v201, v201
	ds_write_b16 v73, v65 offset:288
	v_cvt_pk_bf16_f32 v65, v133, v133
	ds_write_b16 v73, v65 offset:432
	v_cvt_pk_bf16_f32 v65, v134, v134
	ds_write_b16 v73, v65 offset:576
	v_cvt_pk_bf16_f32 v65, v192, v192
	ds_write_b16 v73, v65 offset:720
	v_cvt_pk_bf16_f32 v65, v193, v193
	ds_write_b16 v73, v65 offset:864
	v_cvt_pk_bf16_f32 v65, v194, v194
	ds_write_b16 v73, v65 offset:1008
	v_cvt_pk_bf16_f32 v65, v195, v195
	ds_write_b16 v73, v65 offset:1152
	v_cvt_pk_bf16_f32 v65, v196, v196
	ds_write_b16 v73, v65 offset:1296
	v_cvt_pk_bf16_f32 v65, v197, v197
	ds_write_b16 v73, v65 offset:1440
	v_cvt_pk_bf16_f32 v65, v198, v198
	ds_write_b16 v73, v65 offset:1584
	v_cvt_pk_bf16_f32 v65, v202, v202
	ds_write_b16 v73, v65 offset:1728
	v_cvt_pk_bf16_f32 v65, v203, v203
	ds_write_b16 v73, v65 offset:1872
	v_cvt_pk_bf16_f32 v65, v204, v204
	ds_write_b16 v73, v65 offset:2016
	v_cvt_pk_bf16_f32 v65, v205, v205
	ds_write_b16 v73, v65 offset:2160
	v_cvt_pk_bf16_f32 v65, v206, v206
	ds_write_b16 v73, v65 offset:2304
	v_cvt_pk_bf16_f32 v65, v207, v207
	ds_write_b16 v73, v65 offset:2448
	v_cvt_pk_bf16_f32 v65, v208, v208
	ds_write_b16 v73, v65 offset:2592
	v_cvt_pk_bf16_f32 v65, v209, v209
	ds_write_b16 v73, v65 offset:2736
	v_cvt_pk_bf16_f32 v65, v210, v210
	ds_write_b16 v73, v65 offset:2880
	v_cvt_pk_bf16_f32 v65, v211, v211
	ds_write_b16 v73, v65 offset:3024
	v_cvt_pk_bf16_f32 v65, v212, v212
	ds_write_b16 v73, v65 offset:3168
	v_cvt_pk_bf16_f32 v65, v213, v213
	ds_write_b16 v73, v65 offset:3312
	v_cvt_pk_bf16_f32 v65, v214, v214
	ds_write_b16 v73, v65 offset:3456
	v_cvt_pk_bf16_f32 v65, v215, v215
	ds_write_b16 v73, v65 offset:3600
	v_cvt_pk_bf16_f32 v65, v216, v216
	ds_write_b16 v73, v65 offset:3744
	v_cvt_pk_bf16_f32 v65, v217, v217
	ds_write_b16 v73, v65 offset:3888
	v_cvt_pk_bf16_f32 v65, v218, v218
	ds_write_b16 v73, v65 offset:4032
	v_cvt_pk_bf16_f32 v65, v219, v219
	ds_write_b16 v73, v65 offset:4176
	v_cvt_pk_bf16_f32 v65, v220, v220
	ds_write_b16 v73, v65 offset:4320
	v_cvt_pk_bf16_f32 v65, v221, v221
	ds_write_b16 v73, v65 offset:4464
	v_cvt_pk_bf16_f32 v65, v222, v222
	ds_write_b16 v73, v65 offset:4608
	v_cvt_pk_bf16_f32 v65, v223, v223
	ds_write_b16 v73, v65 offset:4752
	v_cvt_pk_bf16_f32 v65, v224, v224
	ds_write_b16 v73, v65 offset:4896
	v_cvt_pk_bf16_f32 v65, v225, v225
	ds_write_b16 v73, v65 offset:5040
	v_cvt_pk_bf16_f32 v65, v226, v226
	ds_write_b16 v73, v65 offset:5184
	v_cvt_pk_bf16_f32 v65, v227, v227
	ds_write_b16 v73, v65 offset:5328
	v_cvt_pk_bf16_f32 v65, v228, v228
	ds_write_b16 v73, v65 offset:5472
	v_cvt_pk_bf16_f32 v65, v229, v229
	ds_write_b16 v73, v65 offset:5616
	v_cvt_pk_bf16_f32 v65, v230, v230
	ds_write_b16 v73, v65 offset:5760
	v_cvt_pk_bf16_f32 v65, v231, v231
	ds_write_b16 v73, v65 offset:5904
	v_cvt_pk_bf16_f32 v65, v232, v232
	ds_write_b16 v73, v65 offset:6048
	v_cvt_pk_bf16_f32 v65, v233, v233
	ds_write_b16 v73, v65 offset:6192
	v_cvt_pk_bf16_f32 v65, v234, v234
	ds_write_b16 v73, v65 offset:6336
	v_cvt_pk_bf16_f32 v65, v235, v235
	ds_write_b16 v73, v65 offset:6480
	v_cvt_pk_bf16_f32 v65, v236, v236
	ds_write_b16 v73, v65 offset:6624
	v_cvt_pk_bf16_f32 v65, v237, v237
	ds_write_b16 v73, v65 offset:6768
	v_cvt_pk_bf16_f32 v65, v238, v238
	ds_write_b16 v73, v65 offset:6912
	v_cvt_pk_bf16_f32 v65, v239, v239
	ds_write_b16 v73, v65 offset:7056
	v_cvt_pk_bf16_f32 v65, v240, v240
	ds_write_b16 v73, v65 offset:7200
	v_cvt_pk_bf16_f32 v65, v241, v241
	ds_write_b16 v73, v65 offset:7344
	v_cvt_pk_bf16_f32 v65, v242, v242
	ds_write_b16 v73, v65 offset:7488
	v_cvt_pk_bf16_f32 v65, v243, v243
	ds_write_b16 v73, v65 offset:7632
	v_cvt_pk_bf16_f32 v65, v244, v244
	ds_write_b16 v73, v65 offset:7776
	v_cvt_pk_bf16_f32 v65, v245, v245
	ds_write_b16 v73, v65 offset:7920
	v_cvt_pk_bf16_f32 v65, v246, v246
	ds_write_b16 v73, v65 offset:8064
	v_cvt_pk_bf16_f32 v65, v247, v247
	ds_write_b16 v73, v65 offset:8208
	v_cvt_pk_bf16_f32 v65, v248, v248
	ds_write_b16 v73, v65 offset:8352
	v_cvt_pk_bf16_f32 v65, v249, v249
	ds_write_b16 v73, v65 offset:8496
	v_cvt_pk_bf16_f32 v65, v250, v250
	ds_write_b16 v73, v65 offset:8640
	v_cvt_pk_bf16_f32 v65, v251, v251
	ds_write_b16 v73, v65 offset:8784
	v_cvt_pk_bf16_f32 v65, v252, v252
	ds_write_b16 v73, v65 offset:8928
	v_cvt_pk_bf16_f32 v65, v97, v97
	ds_write_b16 v73, v65 offset:9072
	s_waitcnt vmcnt(3)
	v_mul_f32_e32 v65, 0xbfb8aa3b, v66
	v_exp_f32_e32 v97, v65
	s_waitcnt vmcnt(2)
	v_mul_f32_e32 v66, 0xbfb8aa3b, v67
	v_exp_f32_e32 v100, v66
	s_waitcnt vmcnt(1)
	v_mul_f32_e32 v67, 0xbfb8aa3b, v68
	s_waitcnt vmcnt(0)
	v_mul_f32_e32 v64, 0xbfb8aa3b, v64
	v_exp_f32_e32 v101, v67
	v_add_f32_e32 v134, 1.0, v97
	v_exp_f32_e32 v133, v64
	v_frexp_mant_f32_e32 v139, v134
	v_cvt_f64_f32_e32 v[64:65], v134
	v_add_f32_e32 v135, 1.0, v100
	v_frexp_exp_i32_f64_e32 v64, v[64:65]
	v_cmp_gt_f32_e32 vcc, s88, v139
	v_frexp_mant_f32_e32 v141, v135
	v_cvt_f64_f32_e32 v[66:67], v135
	v_subbrev_co_u32_e32 v64, vcc, 0, v64, vcc
	v_add_f32_e32 v136, 1.0, v101
	v_frexp_exp_i32_f64_e32 v66, v[66:67]
	v_cmp_gt_f32_e32 vcc, s88, v141
	v_frexp_mant_f32_e32 v143, v136
	v_cvt_f64_f32_e32 v[68:69], v136
	v_subbrev_co_u32_e32 v66, vcc, 0, v66, vcc
	v_add_f32_e32 v137, 1.0, v133
	v_add_f32_e32 v138, -1.0, v134
	v_frexp_exp_i32_f64_e32 v68, v[68:69]
	v_cmp_gt_f32_e32 vcc, s88, v143
	v_add_f32_e32 v140, -1.0, v135
	v_frexp_mant_f32_e32 v145, v137
	v_cvt_f64_f32_e32 v[70:71], v137
	v_sub_f32_e32 v146, v138, v134
	v_subbrev_co_u32_e32 v68, vcc, 0, v68, vcc
	v_add_f32_e32 v142, -1.0, v136
	v_add_f32_e32 v144, -1.0, v137
	v_sub_f32_e32 v138, v97, v138
	v_sub_f32_e32 v65, v140, v135
	v_frexp_exp_i32_f64_e32 v70, v[70:71]
	v_add_f32_e32 v71, 1.0, v146
	v_cmp_gt_f32_e32 vcc, s88, v145
	v_sub_f32_e32 v140, v100, v140
	v_sub_f32_e32 v67, v142, v136
	v_sub_f32_e32 v69, v144, v137
	v_add_f32_e32 v65, 1.0, v65
	v_subbrev_co_u32_e32 v70, vcc, 0, v70, vcc
	v_add_f32_e32 v71, v138, v71
	v_sub_u32_e32 v138, 0, v64
	v_sub_f32_e32 v142, v101, v142
	v_sub_f32_e32 v144, v133, v144
	v_add_f32_e32 v67, 1.0, v67
	v_add_f32_e32 v69, 1.0, v69
	v_add_f32_e32 v65, v140, v65
	v_sub_u32_e32 v139, 0, v66
	v_sub_u32_e32 v140, 0, v68
	v_sub_u32_e32 v141, 0, v70
	v_cvt_f32_i32_e32 v70, v70
	v_ldexp_f32 v134, v134, v138
	v_cvt_f32_i32_e32 v64, v64
	v_add_f32_e32 v67, v142, v67
	v_add_f32_e32 v69, v144, v69
	v_ldexp_f32 v71, v71, v138
	v_ldexp_f32 v135, v135, v139
	v_ldexp_f32 v65, v65, v139
	v_ldexp_f32 v136, v136, v140
	v_ldexp_f32 v137, v137, v141
	v_add_f32_e32 v138, -1.0, v134
	v_add_f32_e32 v139, 1.0, v134
	v_cvt_f32_i32_e32 v66, v66
	v_cvt_f32_i32_e32 v68, v68
	v_ldexp_f32 v67, v67, v140
	v_ldexp_f32 v69, v69, v141
	v_add_f32_e32 v140, -1.0, v135
	v_add_f32_e32 v141, 1.0, v135
	v_add_f32_e32 v142, -1.0, v136
	v_add_f32_e32 v143, 1.0, v136
	v_add_f32_e32 v144, -1.0, v137
	v_add_f32_e32 v145, 1.0, v137
	v_add_f32_e32 v146, 1.0, v138
	v_add_f32_e32 v147, -1.0, v139
	v_add_f32_e32 v148, 1.0, v140
	v_add_f32_e32 v149, -1.0, v141
	v_add_f32_e32 v150, 1.0, v142
	v_add_f32_e32 v151, -1.0, v143
	v_add_f32_e32 v152, 1.0, v144
	v_add_f32_e32 v153, -1.0, v145
	v_sub_f32_e32 v146, v134, v146
	v_sub_f32_e32 v134, v134, v147
	v_sub_f32_e32 v148, v135, v148
	v_sub_f32_e32 v135, v135, v149
	v_sub_f32_e32 v150, v136, v150
	v_sub_f32_e32 v136, v136, v151
	v_sub_f32_e32 v152, v137, v152
	v_sub_f32_e32 v137, v137, v153
	v_mul_f32_e32 v153, 0x3f317218, v70
	v_add_f32_e32 v146, v71, v146
	v_add_f32_e32 v71, v71, v134
	v_mul_f32_e32 v147, 0x3f317218, v64
	v_add_f32_e32 v148, v65, v148
	v_add_f32_e32 v65, v65, v135
	v_add_f32_e32 v150, v67, v150
	v_add_f32_e32 v67, v67, v136
	v_add_f32_e32 v152, v69, v152
	v_add_f32_e32 v69, v69, v137
	v_fma_f32 v137, v70, s89, -v153
	v_add_f32_e32 v154, v138, v146
	v_add_f32_e32 v155, v139, v71
	v_mul_f32_e32 v149, 0x3f317218, v66
	v_mul_f32_e32 v151, 0x3f317218, v68
	v_fma_f32 v134, v64, s89, -v147
	v_add_f32_e32 v156, v141, v65
	v_add_f32_e32 v157, v143, v67
	v_fmac_f32_e32 v137, 0xb102e308, v70
	v_sub_f32_e32 v70, v154, v138
	v_sub_f32_e32 v138, v155, v139
	v_rcp_f32_e32 v139, v155
	v_fma_f32 v135, v66, s89, -v149
	v_fma_f32 v136, v68, s89, -v151
	v_fmac_f32_e32 v134, 0xb102e308, v64
	v_add_f32_e32 v158, v145, v69
	v_rcp_f32_e32 v160, v156
	v_rcp_f32_e32 v162, v157
	v_fmac_f32_e32 v135, 0xb102e308, v66
	v_fmac_f32_e32 v136, 0xb102e308, v68
	v_add_f32_e32 v159, v147, v134
	v_rcp_f32_e32 v164, v158
	v_sub_f32_e32 v141, v156, v141
	v_add_f32_e32 v161, v149, v135
	v_sub_f32_e32 v143, v157, v143
	v_add_f32_e32 v163, v151, v136
	v_sub_f32_e32 v71, v71, v138
	v_sub_f32_e32 v138, v159, v147
	v_add_f32_e32 v64, v140, v148
	v_add_f32_e32 v66, v142, v150
	v_sub_f32_e32 v145, v158, v145
	v_add_f32_e32 v165, v153, v137
	v_sub_f32_e32 v65, v65, v141
	v_sub_f32_e32 v141, v161, v149
	v_sub_f32_e32 v67, v67, v143
	v_sub_f32_e32 v143, v163, v151
	v_sub_f32_e32 v134, v134, v138
	v_mul_f32_e32 v138, v154, v139
	v_add_f32_e32 v68, v144, v152
	v_sub_f32_e32 v140, v64, v140
	v_sub_f32_e32 v142, v66, v142
	v_sub_f32_e32 v70, v146, v70
	v_sub_f32_e32 v69, v69, v145
	v_sub_f32_e32 v145, v165, v153
	v_sub_f32_e32 v135, v135, v141
	v_sub_f32_e32 v136, v136, v143
	v_mul_f32_e32 v141, v64, v160
	v_mul_f32_e32 v143, v66, v162
	v_mul_f32_e32 v146, v155, v138
	v_sub_f32_e32 v144, v68, v144
	v_sub_f32_e32 v140, v148, v140
	v_sub_f32_e32 v142, v150, v142
	v_sub_f32_e32 v137, v137, v145
	v_mul_f32_e32 v145, v68, v164
	v_mul_f32_e32 v147, v156, v141
	v_mul_f32_e32 v148, v157, v143
	v_fma_f32 v150, v138, v155, -v146
	v_sub_f32_e32 v144, v152, v144
	v_mul_f32_e32 v149, v158, v145
	v_fma_f32 v151, v141, v156, -v147
	v_fma_f32 v152, v143, v157, -v148
	v_fmac_f32_e32 v150, v138, v71
	v_fma_f32 v153, v145, v158, -v149
	v_fmac_f32_e32 v151, v141, v65
	v_fmac_f32_e32 v152, v143, v67
	v_add_f32_e32 v166, v146, v150
	v_fmac_f32_e32 v153, v145, v69
	v_add_f32_e32 v167, v147, v151
	v_add_f32_e32 v168, v148, v152
	v_sub_f32_e32 v170, v154, v166
	v_add_f32_e32 v169, v149, v153
	v_sub_f32_e32 v146, v166, v146
	v_sub_f32_e32 v171, v64, v167
	v_sub_f32_e32 v172, v66, v168
	v_sub_f32_e32 v154, v154, v170
	v_sub_f32_e32 v173, v68, v169
	v_sub_f32_e32 v146, v146, v150
	v_sub_f32_e32 v64, v64, v171
	v_sub_f32_e32 v66, v66, v172
	v_sub_f32_e32 v150, v154, v166
	v_sub_f32_e32 v147, v167, v147
	v_sub_f32_e32 v148, v168, v148
	v_sub_f32_e32 v68, v68, v173
	v_sub_f32_e32 v64, v64, v167
	v_sub_f32_e32 v66, v66, v168
	v_add_f32_e32 v70, v70, v150
	v_sub_f32_e32 v149, v169, v149
	v_sub_f32_e32 v147, v147, v151
	v_sub_f32_e32 v148, v148, v152
	v_sub_f32_e32 v68, v68, v169
	v_add_f32_e32 v64, v140, v64
	v_add_f32_e32 v66, v142, v66
	v_add_f32_e32 v70, v146, v70
	v_sub_f32_e32 v149, v149, v153
	v_add_f32_e32 v68, v144, v68
	v_add_f32_e32 v64, v147, v64
	v_add_f32_e32 v66, v148, v66
	v_add_f32_e32 v140, v170, v70
	v_add_f32_e32 v68, v149, v68
	v_add_f32_e32 v142, v171, v64
	v_add_f32_e32 v144, v172, v66
	v_mul_f32_e32 v147, v139, v140
	v_add_f32_e32 v146, v173, v68
	v_sub_f32_e32 v148, v170, v140
	v_mul_f32_e32 v149, v160, v142
	v_mul_f32_e32 v151, v162, v144
	v_mul_f32_e32 v166, v155, v147
	v_sub_f32_e32 v150, v171, v142
	v_sub_f32_e32 v152, v172, v144
	v_mul_f32_e32 v153, v164, v146
	v_add_f32_e32 v70, v70, v148
	v_add_f32_e32 v148, v138, v147
	v_mul_f32_e32 v167, v156, v149
	v_mul_f32_e32 v168, v157, v151
	v_fma_f32 v155, v147, v155, -v166
	v_sub_f32_e32 v154, v173, v146
	v_add_f32_e32 v64, v64, v150
	v_add_f32_e32 v150, v141, v149
	v_add_f32_e32 v66, v66, v152
	v_add_f32_e32 v152, v143, v151
	v_mul_f32_e32 v169, v158, v153
	v_sub_f32_e32 v138, v148, v138
	v_fma_f32 v156, v149, v156, -v167
	v_fma_f32 v157, v151, v157, -v168
	v_fmac_f32_e32 v155, v147, v71
	v_add_f32_e32 v68, v68, v154
	v_add_f32_e32 v154, v145, v153
	v_sub_f32_e32 v141, v150, v141
	v_sub_f32_e32 v143, v152, v143
	v_fma_f32 v158, v153, v158, -v169
	v_sub_f32_e32 v71, v147, v138
	v_fmac_f32_e32 v156, v149, v65
	v_fmac_f32_e32 v157, v151, v67
	v_add_f32_e32 v138, v166, v155
	v_sub_f32_e32 v145, v154, v145
	v_sub_f32_e32 v65, v149, v141
	v_sub_f32_e32 v67, v151, v143
	v_fmac_f32_e32 v158, v153, v69
	v_add_f32_e32 v141, v167, v156
	v_add_f32_e32 v143, v168, v157
	v_sub_f32_e32 v149, v140, v138
	v_sub_f32_e32 v69, v153, v145
	v_add_f32_e32 v145, v169, v158
	v_sub_f32_e32 v151, v141, v167
	v_sub_f32_e32 v153, v142, v141
	v_sub_f32_e32 v167, v144, v143
	v_sub_f32_e32 v140, v140, v149
	v_sub_f32_e32 v147, v138, v166
	v_sub_f32_e32 v166, v143, v168
	v_sub_f32_e32 v168, v145, v169
	v_sub_f32_e32 v169, v146, v145
	v_sub_f32_e32 v142, v142, v153
	v_sub_f32_e32 v144, v144, v167
	v_sub_f32_e32 v138, v140, v138
	v_sub_f32_e32 v147, v147, v155
	v_sub_f32_e32 v146, v146, v169
	v_sub_f32_e32 v140, v142, v141
	v_sub_f32_e32 v141, v144, v143
	v_add_f32_e32 v70, v70, v138
	v_sub_f32_e32 v151, v151, v156
	v_sub_f32_e32 v155, v166, v157
	v_sub_f32_e32 v142, v146, v145
	v_add_f32_e32 v64, v64, v140
	v_add_f32_e32 v66, v66, v141
	v_add_f32_e32 v70, v147, v70
	v_sub_f32_e32 v156, v168, v158
	v_add_f32_e32 v68, v68, v142
	v_add_f32_e32 v64, v151, v64
	v_add_f32_e32 v66, v155, v66
	v_add_f32_e32 v70, v149, v70
	v_add_f32_e32 v68, v156, v68
	v_add_f32_e32 v64, v153, v64
	v_add_f32_e32 v66, v167, v66
	v_mul_f32_e32 v70, v139, v70
	v_add_f32_e32 v68, v169, v68
	v_mul_f32_e32 v64, v160, v64
	v_mul_f32_e32 v66, v162, v66
	v_add_f32_e32 v70, v71, v70
	v_mul_f32_e32 v68, v164, v68
	v_add_f32_e32 v64, v65, v64
	v_add_f32_e32 v65, v67, v66
	v_add_f32_e32 v67, v148, v70
	v_add_f32_e32 v66, v69, v68
	v_add_f32_e32 v68, v150, v64
	v_mul_f32_e32 v138, v67, v67
	v_add_f32_e32 v69, v152, v65
	v_sub_f32_e32 v139, v67, v148
	v_mul_f32_e32 v141, v68, v68
	v_sub_f32_e32 v142, v68, v150
	v_fmamk_f32 v150, v138, 0x3e9b6dac, v123
	v_add_f32_e32 v71, v154, v66
	v_ldexp_f32 v140, v67, 1
	v_mul_f32_e32 v144, v69, v69
	v_sub_f32_e32 v70, v70, v139
	v_mul_f32_e32 v67, v67, v138
	v_fmamk_f32 v139, v141, 0x3e9b6dac, v123
	v_fmaak_f32 v138, v138, v150, 0x3f2aaada
	v_ldexp_f32 v143, v68, 1
	v_sub_f32_e32 v145, v69, v152
	v_mul_f32_e32 v147, v71, v71
	v_sub_f32_e32 v64, v64, v142
	v_mul_f32_e32 v68, v68, v141
	v_fmamk_f32 v142, v144, 0x3e9b6dac, v123
	v_fmaak_f32 v139, v141, v139, 0x3f2aaada
	v_mul_f32_e32 v67, v67, v138
	v_ldexp_f32 v146, v69, 1
	v_sub_f32_e32 v65, v65, v145
	v_mul_f32_e32 v69, v69, v144
	v_fmamk_f32 v145, v147, 0x3e9b6dac, v123
	v_fmaak_f32 v141, v144, v142, 0x3f2aaada
	v_mul_f32_e32 v68, v68, v139
	v_add_f32_e32 v138, v140, v67
	v_sub_f32_e32 v148, v71, v154
	v_ldexp_f32 v149, v71, 1
	v_mul_f32_e32 v71, v71, v147
	v_fmaak_f32 v142, v147, v145, 0x3f2aaada
	v_mul_f32_e32 v69, v69, v141
	v_add_f32_e32 v139, v143, v68
	v_sub_f32_e32 v140, v138, v140
	v_ldexp_f32 v70, v70, 1
	v_mul_f32_e32 v71, v71, v142
	v_add_f32_e32 v141, v146, v69
	v_sub_f32_e32 v143, v139, v143
	v_sub_f32_e32 v67, v67, v140
	v_ldexp_f32 v64, v64, 1
	v_add_f32_e32 v142, v149, v71
	v_sub_f32_e32 v144, v141, v146
	v_sub_f32_e32 v68, v68, v143
	v_add_f32_e32 v67, v70, v67
	v_sub_f32_e32 v66, v66, v148
	v_ldexp_f32 v65, v65, 1
	v_sub_f32_e32 v145, v142, v149
	v_sub_f32_e32 v69, v69, v144
	v_add_f32_e32 v64, v64, v68
	v_add_f32_e32 v68, v138, v67
	v_ldexp_f32 v66, v66, 1
	v_sub_f32_e32 v71, v71, v145
	v_add_f32_e32 v65, v65, v69
	v_add_f32_e32 v69, v139, v64
	v_sub_f32_e32 v138, v68, v138
	v_add_f32_e32 v140, v159, v68
	v_add_f32_e32 v66, v66, v71
	v_add_f32_e32 v70, v141, v65
	v_sub_f32_e32 v139, v69, v139
	v_add_f32_e32 v143, v161, v69
	v_sub_f32_e32 v67, v67, v138
	v_sub_f32_e32 v138, v140, v159
	v_add_f32_e32 v71, v142, v66
	v_sub_f32_e32 v141, v70, v141
	v_add_f32_e32 v144, v163, v70
	v_sub_f32_e32 v64, v64, v139
	v_sub_f32_e32 v139, v143, v161
	v_sub_f32_e32 v146, v140, v138
	v_sub_f32_e32 v68, v68, v138
	v_add_f32_e32 v138, v134, v67
	v_sub_f32_e32 v142, v71, v142
	v_add_f32_e32 v145, v165, v71
	v_sub_f32_e32 v65, v65, v141
	v_sub_f32_e32 v141, v144, v163
	v_sub_f32_e32 v147, v143, v139
	v_sub_f32_e32 v69, v69, v139
	v_add_f32_e32 v139, v135, v64
	v_sub_f32_e32 v146, v159, v146
	v_sub_f32_e32 v150, v138, v134
	v_sub_f32_e32 v66, v66, v142
	v_sub_f32_e32 v142, v145, v165
	v_sub_f32_e32 v148, v144, v141
	v_sub_f32_e32 v70, v70, v141
	v_add_f32_e32 v141, v136, v65
	v_sub_f32_e32 v147, v161, v147
	v_sub_f32_e32 v151, v139, v135
	v_add_f32_e32 v68, v68, v146
	v_sub_f32_e32 v146, v138, v150
	v_sub_f32_e32 v149, v145, v142
	v_sub_f32_e32 v71, v71, v142
	v_add_f32_e32 v142, v137, v66
	v_sub_f32_e32 v148, v163, v148
	v_sub_f32_e32 v152, v141, v136
	v_sub_f32_e32 v67, v67, v150
	v_add_f32_e32 v69, v69, v147
	v_sub_f32_e32 v147, v139, v151
	v_sub_f32_e32 v134, v134, v146
	v_add_f32_e32 v68, v138, v68
	v_sub_f32_e32 v149, v165, v149
	v_sub_f32_e32 v153, v142, v137
	v_sub_f32_e32 v64, v64, v151
	v_add_f32_e32 v70, v70, v148
	v_sub_f32_e32 v148, v141, v152
	v_sub_f32_e32 v135, v135, v147
	v_add_f32_e32 v69, v139, v69
	v_add_f32_e32 v67, v67, v134
	v_add_f32_e32 v134, v140, v68
	v_sub_f32_e32 v65, v65, v152
	v_add_f32_e32 v71, v71, v149
	v_sub_f32_e32 v149, v142, v153
	v_sub_f32_e32 v136, v136, v148
	v_add_f32_e32 v70, v141, v70
	v_add_f32_e32 v64, v64, v135
	v_add_f32_e32 v135, v143, v69
	v_sub_f32_e32 v138, v134, v140
	v_sub_f32_e32 v66, v66, v153
	v_sub_f32_e32 v137, v137, v149
	v_add_f32_e32 v71, v142, v71
	v_add_f32_e32 v65, v65, v136
	v_add_f32_e32 v136, v144, v70
	v_sub_f32_e32 v139, v135, v143
	v_sub_f32_e32 v68, v68, v138
	v_add_f32_e32 v66, v66, v137
	v_add_f32_e32 v137, v145, v71
	v_sub_f32_e32 v140, v136, v144
	v_sub_f32_e32 v69, v69, v139
	v_add_f32_e32 v67, v67, v68
	v_sub_f32_e32 v141, v137, v145
	v_sub_f32_e32 v70, v70, v140
	v_add_f32_e32 v64, v64, v69
	v_add_f32_e32 v67, v134, v67
	v_cmp_neq_f32_e32 vcc, s90, v97
	v_sub_f32_e32 v71, v71, v141
	v_add_f32_e32 v65, v65, v70
	v_add_f32_e32 v64, v135, v64
	v_cndmask_b32_e32 v67, v126, v67, vcc
	v_cmp_neq_f32_e32 vcc, s90, v100
	v_add_f32_e32 v66, v66, v71
	v_add_f32_e32 v65, v136, v65
	v_cndmask_b32_e32 v64, v126, v64, vcc
	v_cmp_neq_f32_e32 vcc, s90, v101
	v_add_f32_e32 v66, v137, v66
	s_nop 0
	v_cndmask_b32_e32 v65, v126, v65, vcc
	v_cmp_neq_f32_e32 vcc, s90, v133
	s_nop 1
	v_cndmask_b32_e32 v66, v126, v66, vcc
	v_cmp_ngt_f32_e32 vcc, -1.0, v97
	s_nop 1
	v_cndmask_b32_e32 v67, v127, v67, vcc
	v_cmp_ngt_f32_e32 vcc, -1.0, v100
	s_nop 1
	v_cndmask_b32_e32 v64, v127, v64, vcc
	v_cmp_ngt_f32_e32 vcc, -1.0, v101
	s_nop 1
	v_cndmask_b32_e32 v65, v127, v65, vcc
	v_cmp_ngt_f32_e32 vcc, -1.0, v133
	s_nop 1
	v_cndmask_b32_e32 v66, v127, v66, vcc
	v_cmp_neq_f32_e32 vcc, -1.0, v97
	s_nop 1
	v_cndmask_b32_e32 v67, v128, v67, vcc
	v_cmp_neq_f32_e32 vcc, -1.0, v100
	s_nop 1
	v_cndmask_b32_e32 v64, v128, v64, vcc
	v_cmp_neq_f32_e32 vcc, -1.0, v101
	s_nop 1
	v_cndmask_b32_e32 v65, v128, v65, vcc
	v_cmp_neq_f32_e32 vcc, -1.0, v133
	s_nop 1
	v_cndmask_b32_e32 v66, v128, v66, vcc
	v_cmp_lt_f32_e64 vcc, |v97|, s91
	s_nop 1
	v_cndmask_b32_e32 v67, v67, v97, vcc
	v_cmp_lt_f32_e64 vcc, |v100|, s91
	v_mul_f32_e32 v97, 0xc1000000, v67
	s_nop 0
	v_cndmask_b32_e32 v64, v64, v100, vcc
	v_cmp_lt_f32_e64 vcc, |v101|, s91
	s_nop 1
	v_cndmask_b32_e32 v65, v65, v101, vcc
	v_cmp_lt_f32_e64 vcc, |v133|, s91
	v_mul_f32_e32 v134, 0xc1000000, v65
	v_mov_b32_e32 v101, 0
	v_cndmask_b32_e32 v66, v66, v133, vcc
	v_mul_f32_e32 v133, 0xc1000000, v64
	v_mul_f32_e32 v135, 0xc1000000, v66

.LBB0_1053:
	v_lshl_add_u64 v[2:3], v[58:59], 0, s[12:13]
	v_mov_b32_e32 v89, v75
	v_lshl_add_u64 v[2:3], v[2:3], 0, v[88:89]
	v_mov_b32_e32 v91, v75
	v_lshl_add_u64 v[8:9], v[2:3], 0, v[90:91]
	v_add_co_u32_e32 v2, vcc, s28, v8
	v_lshl_add_u64 v[52:53], v[8:9], 0, s[18:19]
	s_nop 0
	v_addc_co_u32_e32 v3, vcc, 0, v9, vcc
	global_load_dword v18, v[2:3], off
	global_load_dword v19, v[52:53], off offset:256
	global_load_ushort v133, v[0:1], off
	global_load_ushort v134, v[0:1], off offset:3584
	v_add_co_u32_e32 v2, vcc, s27, v0
	v_mov_b32_e32 v93, v75
	s_nop 0
	v_addc_co_u32_e32 v3, vcc, 0, v1, vcc
	v_add_co_u32_e32 v4, vcc, s30, v0
	v_lshl_add_u64 v[100:101], v[60:61], 0, v[92:93]
	s_nop 0
	v_addc_co_u32_e32 v5, vcc, 0, v1, vcc
	v_add_co_u32_e32 v6, vcc, s31, v0
	s_waitcnt vmcnt(4)
	v_fma_f32 v200, v132, v98, v97
	v_addc_co_u32_e32 v7, vcc, 0, v1, vcc
	v_add_co_u32_e32 v10, vcc, s34, v0
	v_fma_f32 v201, v132, v74, v97
	s_nop 0
	v_addc_co_u32_e32 v11, vcc, 0, v1, vcc
	v_add_co_u32_e32 v12, vcc, s35, v0
	v_fmac_f32_e32 v200, v131, v74
	s_nop 0
	v_addc_co_u32_e32 v13, vcc, 0, v1, vcc
	v_add_co_u32_e32 v14, vcc, s36, v0
	v_fma_f32 v199, v132, v70, v97
	s_nop 0
	v_addc_co_u32_e32 v15, vcc, 0, v1, vcc
	v_add_co_u32_e32 v16, vcc, s37, v0
	v_lshl_add_u64 v[70:71], v[64:65], 0, v[92:93]
	s_nop 0
	v_addc_co_u32_e32 v17, vcc, 0, v1, vcc
	global_load_ushort v142, v[2:3], off offset:3072
	global_load_ushort v139, v[4:5], off offset:2560
	global_load_ushort v138, v[6:7], off offset:2048
	global_load_ushort v135, v[10:11], off offset:1536
	global_load_ushort v136, v[12:13], off offset:1024
	global_load_ushort v137, v[14:15], off offset:512
	global_load_ushort v140, v[16:17], off
	global_load_ushort v141, v[16:17], off offset:3584
	v_add_co_u32_e32 v2, vcc, s38, v0
	v_lshl_add_u64 v[64:65], v[66:67], 0, v[92:93]
	s_nop 0
	v_addc_co_u32_e32 v3, vcc, 0, v1, vcc
	v_add_co_u32_e32 v4, vcc, s39, v0
	v_fmac_f32_e32 v199, v131, v98
	s_nop 0
	v_addc_co_u32_e32 v5, vcc, 0, v1, vcc
	v_add_co_u32_e32 v6, vcc, s40, v0
	v_fmac_f32_e32 v199, v130, v74
	s_nop 0
	v_addc_co_u32_e32 v7, vcc, 0, v1, vcc
	v_add_co_u32_e32 v10, vcc, s41, v0
	s_lshr_b32 s8, s3, 2
	s_nop 0
	v_addc_co_u32_e32 v11, vcc, 0, v1, vcc
	v_add_co_u32_e32 v12, vcc, s42, v0
	s_and_b32 s8, s8, 63
	s_nop 0
	v_addc_co_u32_e32 v13, vcc, 0, v1, vcc
	v_add_co_u32_e32 v14, vcc, s43, v0
	s_lshl_b64 s[96:97], s[22:23], 22
	s_nop 0
	v_addc_co_u32_e32 v15, vcc, 0, v1, vcc
	v_add_co_u32_e32 v16, vcc, s44, v0
	s_lshl_b32 s8, s8, 16
	s_nop 0
	v_addc_co_u32_e32 v17, vcc, 0, v1, vcc
	global_load_ushort v143, v[2:3], off offset:3072
	global_load_ushort v144, v[4:5], off offset:2560
	global_load_ushort v145, v[6:7], off offset:2048
	global_load_ushort v146, v[10:11], off offset:1536
	global_load_ushort v147, v[12:13], off offset:1024
	global_load_ushort v148, v[14:15], off offset:512
	global_load_ushort v149, v[16:17], off
	global_load_ushort v150, v[16:17], off offset:3584
	v_add_co_u32_e32 v2, vcc, s45, v0
	v_lshl_add_u64 v[202:203], v[94:95], 0, v[82:83]
	s_nop 0
	v_addc_co_u32_e32 v3, vcc, 0, v1, vcc
	v_add_co_u32_e32 v4, vcc, s28, v0
	s_or_b32 s96, s96, s8
	s_nop 0
	v_addc_co_u32_e32 v5, vcc, 0, v1, vcc
	v_add_co_u32_e32 v6, vcc, s48, v0
	v_lshl_add_u64 v[98:99], v[202:203], 0, s[96:97]
	s_nop 0
	v_addc_co_u32_e32 v7, vcc, 0, v1, vcc
	v_add_co_u32_e32 v10, vcc, s29, v0
	s_mov_b32 s95, 0
	s_nop 0
	v_addc_co_u32_e32 v11, vcc, 0, v1, vcc
	v_add_co_u32_e32 v12, vcc, s49, v0
	v_mov_b32_e32 v96, 1.0
	s_nop 0
	v_addc_co_u32_e32 v13, vcc, 0, v1, vcc
	v_add_co_u32_e32 v14, vcc, s50, v0
	s_waitcnt vmcnt(15)
	v_lshlrev_b32_e32 v66, 16, v142
	v_addc_co_u32_e32 v15, vcc, 0, v1, vcc
	v_add_co_u32_e32 v16, vcc, s51, v0
	s_waitcnt vmcnt(12)
	v_lshlrev_b32_e32 v74, 16, v135
	v_addc_co_u32_e32 v17, vcc, 0, v1, vcc
	global_load_ushort v151, v[2:3], off offset:3072
	global_load_ushort v152, v[4:5], off offset:2560
	global_load_ushort v153, v[6:7], off offset:2048
	global_load_ushort v154, v[10:11], off offset:1536
	global_load_ushort v155, v[12:13], off offset:1024
	global_load_ushort v156, v[14:15], off offset:512
	global_load_ushort v157, v[16:17], off
	global_load_ushort v158, v[16:17], off offset:3584
	v_add_co_u32_e32 v2, vcc, s52, v0
	s_waitcnt vmcnt(16)
	v_lshlrev_b32_e32 v135, 16, v141
	v_addc_co_u32_e32 v3, vcc, 0, v1, vcc
	v_add_co_u32_e32 v4, vcc, s53, v0
	v_lshlrev_b32_e32 v67, 16, v139
	s_nop 0
	v_addc_co_u32_e32 v5, vcc, 0, v1, vcc
	v_add_co_u32_e32 v6, vcc, s54, v0
	v_lshlrev_b32_e32 v93, 16, v140
	s_nop 0
	v_addc_co_u32_e32 v7, vcc, 0, v1, vcc
	v_add_co_u32_e32 v10, vcc, s55, v0
	v_fma_f32 v202, v132, v135, v97
	s_nop 0
	v_addc_co_u32_e32 v11, vcc, 0, v1, vcc
	v_add_co_u32_e32 v12, vcc, s56, v0
	s_waitcnt vmcnt(12)
	v_lshlrev_b32_e32 v139, 16, v146
	v_addc_co_u32_e32 v13, vcc, 0, v1, vcc
	v_add_co_u32_e32 v14, vcc, s57, v0
	s_waitcnt vmcnt(10)
	v_lshlrev_b32_e32 v141, 16, v148
	v_addc_co_u32_e32 v15, vcc, 0, v1, vcc
	v_add_co_u32_e32 v16, vcc, s58, v0
	s_waitcnt vmcnt(9)
	v_lshlrev_b32_e32 v142, 16, v149
	v_addc_co_u32_e32 v17, vcc, 0, v1, vcc
	global_load_ushort v159, v[2:3], off offset:3072
	global_load_ushort v160, v[4:5], off offset:2560
	global_load_ushort v161, v[6:7], off offset:2048
	global_load_ushort v162, v[10:11], off offset:1536
	global_load_ushort v163, v[12:13], off offset:1024
	global_load_ushort v164, v[14:15], off offset:512
	global_load_ushort v165, v[16:17], off
	global_load_ushort v166, v[16:17], off offset:3584
	v_add_co_u32_e32 v2, vcc, s59, v0
	v_lshlrev_b32_e32 v140, 16, v147
	s_nop 0
	v_addc_co_u32_e32 v3, vcc, 0, v1, vcc
	v_add_co_u32_e32 v4, vcc, s60, v0
	v_fma_f32 v206, v132, v139, v97
	s_nop 0
	v_addc_co_u32_e32 v5, vcc, 0, v1, vcc
	v_add_co_u32_e32 v6, vcc, s61, v0
	v_fma_f32 v207, v132, v140, v97
	s_nop 0
	v_addc_co_u32_e32 v7, vcc, 0, v1, vcc
	v_add_co_u32_e32 v10, vcc, s62, v0
	v_fma_f32 v208, v132, v141, v97
	s_nop 0
	v_addc_co_u32_e32 v11, vcc, 0, v1, vcc
	v_add_co_u32_e32 v12, vcc, s63, v0
	v_fma_f32 v209, v132, v142, v97
	s_nop 0
	v_addc_co_u32_e32 v13, vcc, 0, v1, vcc
	v_add_co_u32_e32 v14, vcc, s64, v0
	v_fmac_f32_e32 v206, v131, v140
	s_nop 0
	v_addc_co_u32_e32 v15, vcc, 0, v1, vcc
	v_add_co_u32_e32 v16, vcc, s65, v0
	s_waitcnt vmcnt(11)
	v_lshlrev_b32_e32 v148, 16, v155
	v_addc_co_u32_e32 v17, vcc, 0, v1, vcc
	global_load_ushort v167, v[2:3], off offset:3072
	global_load_ushort v168, v[4:5], off offset:2560
	global_load_ushort v169, v[6:7], off offset:2048
	global_load_ushort v170, v[10:11], off offset:1536
	global_load_ushort v171, v[12:13], off offset:1024
	global_load_ushort v172, v[14:15], off offset:512
	global_load_ushort v173, v[16:17], off
	global_load_ushort v174, v[16:17], off offset:3584
	v_add_co_u32_e32 v2, vcc, s66, v0
	s_waitcnt vmcnt(18)
	v_lshlrev_b32_e32 v149, 16, v156
	v_addc_co_u32_e32 v3, vcc, 0, v1, vcc
	v_add_co_u32_e32 v4, vcc, s67, v0
	v_lshlrev_b32_e32 v146, 16, v153
	s_nop 0
	v_addc_co_u32_e32 v5, vcc, 0, v1, vcc
	v_add_co_u32_e32 v6, vcc, s70, v0
	v_lshlrev_b32_e32 v147, 16, v154
	s_nop 0
	v_addc_co_u32_e32 v7, vcc, 0, v1, vcc
	v_add_co_u32_e32 v10, vcc, s71, v0
	v_fma_f32 v213, v132, v146, v97
	s_nop 0
	v_addc_co_u32_e32 v11, vcc, 0, v1, vcc
	v_add_co_u32_e32 v12, vcc, s72, v0
	v_fma_f32 v214, v132, v147, v97
	s_nop 0
	v_addc_co_u32_e32 v13, vcc, 0, v1, vcc
	v_add_co_u32_e32 v14, vcc, s73, v0
	v_fma_f32 v215, v132, v148, v97
	s_nop 0
	v_addc_co_u32_e32 v15, vcc, 0, v1, vcc
	v_add_co_u32_e32 v16, vcc, s74, v0
	v_fma_f32 v217, v132, v149, v97
	s_nop 0
	v_addc_co_u32_e32 v17, vcc, 0, v1, vcc
	global_load_ushort v175, v[2:3], off offset:3072
	global_load_ushort v178, v[4:5], off offset:2560
	global_load_ushort v179, v[6:7], off offset:2048
	global_load_ushort v180, v[10:11], off offset:1536
	global_load_ushort v181, v[12:13], off offset:1024
	global_load_ushort v182, v[14:15], off offset:512
	global_load_ushort v183, v[16:17], off
	global_load_ushort v184, v[16:17], off offset:3584
	v_add_co_u32_e32 v2, vcc, s75, v0
	s_waitcnt vmcnt(22)
	v_lshlrev_b32_e32 v153, 16, v160
	v_addc_co_u32_e32 v3, vcc, 0, v1, vcc
	v_add_co_u32_e32 v4, vcc, s76, v0
	s_waitcnt vmcnt(20)
	v_lshlrev_b32_e32 v155, 16, v162
	v_addc_co_u32_e32 v5, vcc, 0, v1, vcc
	v_add_co_u32_e32 v6, vcc, s77, v0
	s_waitcnt vmcnt(19)
	v_lshlrev_b32_e32 v156, 16, v163
	v_addc_co_u32_e32 v7, vcc, 0, v1, vcc
	v_add_co_u32_e32 v10, vcc, s78, v0
	v_lshlrev_b32_e32 v154, 16, v161
	s_nop 0
	v_addc_co_u32_e32 v11, vcc, 0, v1, vcc
	v_add_co_u32_e32 v12, vcc, s79, v0
	v_fma_f32 v221, v132, v153, v97
	s_nop 0
	v_addc_co_u32_e32 v13, vcc, 0, v1, vcc
	v_add_co_u32_e32 v14, vcc, s80, v0
	v_fma_f32 v222, v132, v154, v97
	s_nop 0
	v_addc_co_u32_e32 v15, vcc, 0, v1, vcc
	v_add_co_u32_e32 v16, vcc, s81, v0
	v_fma_f32 v223, v132, v155, v97
	s_nop 0
	v_addc_co_u32_e32 v17, vcc, 0, v1, vcc
	global_load_ushort v185, v[2:3], off offset:3072
	global_load_ushort v186, v[4:5], off offset:2560
	global_load_ushort v187, v[6:7], off offset:2048
	global_load_ushort v188, v[10:11], off offset:1536
	global_load_ushort v189, v[12:13], off offset:1024
	global_load_ushort v190, v[14:15], off offset:512
	global_load_ushort v191, v[16:17], off
	global_load_ushort v192, v[16:17], off offset:3584
	v_add_co_u32_e32 v2, vcc, s82, v0
	s_waitcnt vmcnt(21)
	v_lshlrev_b32_e32 v162, 16, v169
	v_addc_co_u32_e32 v3, vcc, 0, v1, vcc
	v_add_co_u32_e32 v4, vcc, s83, v0
	s_waitcnt vmcnt(20)
	v_lshlrev_b32_e32 v163, 16, v170
	v_addc_co_u32_e32 v5, vcc, 0, v1, vcc
	v_add_co_u32_e32 v6, vcc, s84, v0
	v_lshlrev_b32_e32 v160, 16, v167
	s_nop 0
	v_addc_co_u32_e32 v7, vcc, 0, v1, vcc
	v_add_co_u32_e32 v10, vcc, s85, v0
	v_lshlrev_b32_e32 v161, 16, v168
	s_nop 0
	v_addc_co_u32_e32 v11, vcc, 0, v1, vcc
	v_add_co_u32_e32 v12, vcc, s86, v0
	s_waitcnt vmcnt(16)
	v_lshlrev_b32_e32 v167, 16, v174
	v_addc_co_u32_e32 v13, vcc, 0, v1, vcc
	v_add_co_u32_e32 v0, vcc, s87, v0
	v_fma_f32 v224, v132, v156, v97
	s_nop 0
	v_addc_co_u32_e32 v1, vcc, 0, v1, vcc
	global_load_ushort v193, v[2:3], off offset:3072
	global_load_ushort v194, v[4:5], off offset:2560
	global_load_ushort v195, v[6:7], off offset:2048
	global_load_ushort v196, v[10:11], off offset:1536
	global_load_ushort v197, v[12:13], off offset:1024
	global_load_ushort v198, v[0:1], off offset:512
	v_cvt_pk_bf16_f32 v0, v18, v19
	global_load_dword v1, v[52:53], off offset:768
	global_load_dword v2, v[52:53], off offset:512
	s_waitcnt vmcnt(0)
	v_cvt_pk_bf16_f32 v1, v2, v1
	global_load_dword v226, v[52:53], off offset:1280
	global_load_dword v227, v[52:53], off offset:1024
	global_load_dword v228, v[52:53], off offset:1792
	global_load_dword v229, v[52:53], off offset:1536
	v_lshl_add_u64 v[4:5], v[62:63], 0, s[12:13]
	v_lshl_add_u64 v[4:5], v[4:5], 0, v[88:89]
	v_lshl_add_u64 v[12:13], v[4:5], 0, v[90:91]
	v_add_co_u32_e32 v4, vcc, s28, v12
	v_lshl_add_u64 v[56:57], v[12:13], 0, s[18:19]
	s_nop 0
	v_addc_co_u32_e32 v5, vcc, 0, v13, vcc
	global_load_dword v230, v[4:5], off
	s_nop 0
	global_load_dword v231, v[56:57], off offset:256
	global_load_dword v232, v[56:57], off offset:768
	global_load_dword v233, v[56:57], off offset:512
	global_load_dword v234, v[56:57], off offset:1280
	global_load_dword v235, v[56:57], off offset:1024
	global_load_dword v236, v[56:57], off offset:1792
	global_load_dword v237, v[56:57], off offset:1536
	v_add_co_u32_e32 v62, vcc, s29, v8
	s_nop 0
	v_addc_co_u32_e32 v63, vcc, 0, v9, vcc
	global_load_dword v238, v[62:63], off offset:256
	global_load_dword v239, v[62:63], off
	global_load_dword v240, v[62:63], off offset:768
	global_load_dword v241, v[62:63], off offset:512
	global_load_dword v242, v[62:63], off offset:1280
	global_load_dword v243, v[62:63], off offset:1024
	global_load_dword v244, v[62:63], off offset:1792
	global_load_dword v245, v[62:63], off offset:1536
	v_add_co_u32_e32 v68, vcc, s29, v12
	s_nop 0
	v_addc_co_u32_e32 v69, vcc, 0, v13, vcc
	global_load_dword v246, v[68:69], off offset:256
	global_load_dword v247, v[68:69], off
	global_load_dword v248, v[68:69], off offset:768
	global_load_dword v249, v[68:69], off offset:512
	global_load_dword v250, v[68:69], off offset:1280
	global_load_dword v251, v[68:69], off offset:1024
	global_load_dword v252, v[68:69], off offset:1792
	global_load_dword v253, v[68:69], off offset:1536
	s_waitcnt vmcnt(0)
	v_cvt_pk_bf16_f32 v2, v227, v226
	v_cvt_pk_bf16_f32 v3, v229, v228
	v_cvt_pk_bf16_f32 v4, v230, v231
	v_cvt_pk_bf16_f32 v5, v233, v232
	v_cvt_pk_bf16_f32 v6, v235, v234
	v_cvt_pk_bf16_f32 v7, v237, v236
	v_cvt_pk_bf16_f32 v8, v239, v238
	v_cvt_pk_bf16_f32 v9, v241, v240
	v_cvt_pk_bf16_f32 v10, v243, v242
	v_cvt_pk_bf16_f32 v11, v245, v244
	v_cvt_pk_bf16_f32 v12, v247, v246
	v_cvt_pk_bf16_f32 v13, v249, v248
	v_cvt_pk_bf16_f32 v14, v251, v250
	v_cvt_pk_bf16_f32 v15, v253, v252
	global_load_dword v226, v[52:53], off offset:320
	global_load_dword v227, v[52:53], off offset:64
	global_load_dword v228, v[52:53], off offset:832
	global_load_dword v229, v[52:53], off offset:576
	global_load_dword v230, v[52:53], off offset:1344
	global_load_dword v231, v[52:53], off offset:1088
	global_load_dword v232, v[52:53], off offset:1856
	global_load_dword v233, v[52:53], off offset:1600
	global_load_dword v234, v[56:57], off offset:320
	global_load_dword v235, v[56:57], off offset:64
	global_load_dword v236, v[56:57], off offset:832
	global_load_dword v237, v[56:57], off offset:576
	global_load_dword v238, v[56:57], off offset:1344
	global_load_dword v239, v[56:57], off offset:1088
	global_load_dword v240, v[56:57], off offset:1856
	global_load_dword v241, v[56:57], off offset:1600
	global_load_dword v242, v[62:63], off offset:320
	global_load_dword v243, v[62:63], off offset:64
	global_load_dword v244, v[62:63], off offset:832
	global_load_dword v245, v[62:63], off offset:576
	global_load_dword v246, v[62:63], off offset:1344
	global_load_dword v247, v[62:63], off offset:1088
	global_load_dword v248, v[62:63], off offset:1856
	global_load_dword v249, v[62:63], off offset:1600
	global_load_dword v250, v[68:69], off offset:320
	global_load_dword v251, v[68:69], off offset:64
	global_load_dword v252, v[68:69], off offset:832
	global_load_dword v253, v[68:69], off offset:576
	s_waitcnt vmcnt(0)
	v_cvt_pk_bf16_f32 v16, v227, v226
	v_cvt_pk_bf16_f32 v17, v229, v228
	v_cvt_pk_bf16_f32 v18, v231, v230
	v_cvt_pk_bf16_f32 v19, v233, v232
	v_cvt_pk_bf16_f32 v20, v235, v234
	v_cvt_pk_bf16_f32 v21, v237, v236
	v_cvt_pk_bf16_f32 v22, v239, v238
	v_cvt_pk_bf16_f32 v23, v241, v240
	v_cvt_pk_bf16_f32 v24, v243, v242
	v_cvt_pk_bf16_f32 v25, v245, v244
	v_cvt_pk_bf16_f32 v26, v247, v246
	v_cvt_pk_bf16_f32 v27, v249, v248
	v_cvt_pk_bf16_f32 v28, v251, v250
	v_cvt_pk_bf16_f32 v29, v253, v252
	global_load_dword v226, v[68:69], off offset:1344
	global_load_dword v227, v[68:69], off offset:1088
	global_load_dword v228, v[68:69], off offset:1856
	global_load_dword v229, v[68:69], off offset:1600
	global_load_dword v230, v[52:53], off offset:384
	global_load_dword v231, v[52:53], off offset:128
	global_load_dword v232, v[52:53], off offset:896
	global_load_dword v233, v[52:53], off offset:640
	global_load_dword v234, v[52:53], off offset:1408
	global_load_dword v235, v[52:53], off offset:1152
	global_load_dword v236, v[52:53], off offset:1920
	global_load_dword v237, v[52:53], off offset:1664
	global_load_dword v238, v[56:57], off offset:384
	global_load_dword v239, v[56:57], off offset:128
	global_load_dword v240, v[56:57], off offset:896
	global_load_dword v241, v[56:57], off offset:640
	global_load_dword v242, v[56:57], off offset:1408
	global_load_dword v243, v[56:57], off offset:1152
	global_load_dword v244, v[56:57], off offset:1920
	global_load_dword v245, v[56:57], off offset:1664
	global_load_dword v246, v[62:63], off offset:384
	global_load_dword v247, v[62:63], off offset:128
	global_load_dword v248, v[62:63], off offset:896
	global_load_dword v249, v[62:63], off offset:640
	global_load_dword v250, v[62:63], off offset:1408
	global_load_dword v251, v[62:63], off offset:1152
	global_load_dword v252, v[62:63], off offset:1920
	global_load_dword v253, v[62:63], off offset:1664
	s_waitcnt vmcnt(0)
	v_cvt_pk_bf16_f32 v30, v227, v226
	v_cvt_pk_bf16_f32 v31, v229, v228
	v_cvt_pk_bf16_f32 v32, v231, v230
	v_cvt_pk_bf16_f32 v33, v233, v232
	v_cvt_pk_bf16_f32 v34, v235, v234
	v_cvt_pk_bf16_f32 v35, v237, v236
	v_cvt_pk_bf16_f32 v36, v239, v238
	v_cvt_pk_bf16_f32 v37, v241, v240
	v_cvt_pk_bf16_f32 v38, v243, v242
	v_cvt_pk_bf16_f32 v39, v245, v244
	v_cvt_pk_bf16_f32 v40, v247, v246
	v_cvt_pk_bf16_f32 v41, v249, v248
	v_cvt_pk_bf16_f32 v42, v251, v250
	v_cvt_pk_bf16_f32 v43, v253, v252
	global_load_dword v226, v[68:69], off offset:384
	global_load_dword v227, v[68:69], off offset:128
	global_load_dword v228, v[68:69], off offset:896
	global_load_dword v229, v[68:69], off offset:640
	global_load_dword v230, v[68:69], off offset:1408
	global_load_dword v231, v[68:69], off offset:1152
	global_load_dword v232, v[68:69], off offset:1920
	global_load_dword v233, v[68:69], off offset:1664
	global_load_dword v234, v[52:53], off offset:448
	global_load_dword v235, v[52:53], off offset:192
	global_load_dword v236, v[52:53], off offset:960
	global_load_dword v237, v[52:53], off offset:704
	global_load_dword v238, v[52:53], off offset:1472
	global_load_dword v239, v[52:53], off offset:1216
	global_load_dword v240, v[52:53], off offset:1984
	s_nop 0
	global_load_dword v241, v[52:53], off offset:1728
	global_load_dword v242, v[56:57], off offset:448
	global_load_dword v243, v[56:57], off offset:192
	global_load_dword v244, v[56:57], off offset:960
	global_load_dword v245, v[56:57], off offset:704
	global_load_dword v246, v[56:57], off offset:1472
	global_load_dword v247, v[56:57], off offset:1216
	global_load_dword v248, v[56:57], off offset:1984
	s_nop 0
	global_load_dword v249, v[56:57], off offset:1728
	global_load_dword v250, v[62:63], off offset:448
	global_load_dword v251, v[62:63], off offset:192
	global_load_dword v252, v[62:63], off offset:960
	global_load_dword v253, v[62:63], off offset:704
	s_waitcnt vmcnt(0)
	v_cvt_pk_bf16_f32 v44, v227, v226
	v_cvt_pk_bf16_f32 v45, v229, v228
	v_cvt_pk_bf16_f32 v46, v231, v230
	v_cvt_pk_bf16_f32 v47, v233, v232
	v_cvt_pk_bf16_f32 v48, v235, v234
	v_cvt_pk_bf16_f32 v49, v237, v236
	v_cvt_pk_bf16_f32 v50, v239, v238
	v_cvt_pk_bf16_f32 v51, v241, v240
	v_cvt_pk_bf16_f32 v52, v243, v242
	v_cvt_pk_bf16_f32 v53, v245, v244
	v_cvt_pk_bf16_f32 v54, v247, v246
	v_cvt_pk_bf16_f32 v55, v249, v248
	v_cvt_pk_bf16_f32 v56, v251, v250
	v_cvt_pk_bf16_f32 v57, v253, v252
	global_load_dword v226, v[62:63], off offset:1472
	global_load_dword v227, v[62:63], off offset:1216
	global_load_dword v228, v[62:63], off offset:1984
	s_nop 0
	global_load_dword v229, v[62:63], off offset:1728
	global_load_dword v230, v[68:69], off offset:448
	global_load_dword v231, v[68:69], off offset:192
	v_lshlrev_b32_e32 v62, 16, v133
	v_lshlrev_b32_e32 v63, 16, v134
	v_fmac_f32_e32 v200, v130, v62
	v_fmac_f32_e32 v201, v131, v62
	v_fma_f32 v133, v132, v62, v97
	v_fma_f32 v134, v132, v63, v97
	v_fmac_f32_e32 v200, v129, v63
	v_fmac_f32_e32 v201, v130, v63
	v_fmac_f32_e32 v133, v131, v63
	global_load_dword v232, v[68:69], off offset:960
	global_load_dword v233, v[68:69], off offset:704
	v_lshlrev_b32_e32 v169, 16, v178
	v_lshlrev_b32_e32 v178, 16, v185
	v_lshlrev_b32_e32 v185, 16, v192
	v_fmac_f32_e32 v134, v131, v66
	v_fma_f32 v192, v132, v66, v97
	v_fmac_f32_e32 v201, v129, v66
	v_fmac_f32_e32 v133, v130, v66
	s_waitcnt vmcnt(0)
	v_cvt_pk_bf16_f32 v58, v227, v226
	v_cvt_pk_bf16_f32 v59, v229, v228
	v_cvt_pk_bf16_f32 v60, v231, v230
	v_cvt_pk_bf16_f32 v61, v233, v232
	global_load_dword v63, v[68:69], off offset:1472
	global_load_dword v66, v[68:69], off offset:1216
	v_fmac_f32_e32 v199, v129, v62
	v_lshlrev_b32_e32 v62, 16, v138
	v_lshlrev_b32_e32 v170, 16, v179
	v_lshlrev_b32_e32 v179, 16, v186
	v_lshlrev_b32_e32 v186, 16, v193
	v_fma_f32 v193, v132, v67, v97
	v_fmac_f32_e32 v134, v130, v67
	v_fmac_f32_e32 v192, v131, v67
	v_lshlrev_b32_e32 v89, 16, v136
	v_lshlrev_b32_e32 v136, 16, v143
	v_lshlrev_b32_e32 v143, 16, v150
	v_lshlrev_b32_e32 v150, 16, v157
	v_lshlrev_b32_e32 v157, 16, v164
	v_lshlrev_b32_e32 v164, 16, v171
	v_lshlrev_b32_e32 v171, 16, v180
	v_lshlrev_b32_e32 v180, 16, v187
	v_lshlrev_b32_e32 v187, 16, v194
	v_fma_f32 v194, v132, v62, v97
	v_fmac_f32_e32 v193, v131, v62
	v_fmac_f32_e32 v134, v129, v62
	v_fmac_f32_e32 v192, v130, v62
	s_waitcnt vmcnt(0)
	v_cvt_pk_bf16_f32 v62, v66, v63
	global_load_dword v63, v[68:69], off offset:1984
	global_load_dword v66, v[68:69], off offset:1728
	v_lshlrev_b32_e32 v91, 16, v137
	v_lshlrev_b32_e32 v137, 16, v144
	v_lshlrev_b32_e32 v138, 16, v145
	v_lshlrev_b32_e32 v144, 16, v151
	v_lshlrev_b32_e32 v145, 16, v152
	v_lshlrev_b32_e32 v151, 16, v158
	v_lshlrev_b32_e32 v152, 16, v159
	v_lshlrev_b32_e32 v158, 16, v165
	v_lshlrev_b32_e32 v159, 16, v166
	v_lshlrev_b32_e32 v165, 16, v172
	v_lshlrev_b32_e32 v166, 16, v173
	v_lshlrev_b32_e32 v168, 16, v175
	v_lshlrev_b32_e32 v172, 16, v181
	v_lshlrev_b32_e32 v173, 16, v182
	v_lshlrev_b32_e32 v174, 16, v183
	v_lshlrev_b32_e32 v175, 16, v184
	v_lshlrev_b32_e32 v181, 16, v188
	v_lshlrev_b32_e32 v182, 16, v189
	v_lshlrev_b32_e32 v183, 16, v190
	v_lshlrev_b32_e32 v184, 16, v191
	v_lshlrev_b32_e32 v188, 16, v195
	v_lshlrev_b32_e32 v189, 16, v196
	v_lshlrev_b32_e32 v190, 16, v197
	v_lshlrev_b32_e32 v191, 16, v198
	v_fma_f32 v195, v132, v74, v97
	v_fma_f32 v196, v132, v89, v97
	v_fma_f32 v197, v132, v91, v97
	v_fma_f32 v198, v132, v93, v97
	v_fma_f32 v203, v132, v136, v97
	v_fma_f32 v204, v132, v137, v97
	v_fma_f32 v205, v132, v138, v97
	v_fma_f32 v210, v132, v143, v97
	v_fma_f32 v211, v132, v144, v97
	v_fma_f32 v212, v132, v145, v97
	v_fma_f32 v218, v132, v150, v97
	v_fma_f32 v219, v132, v151, v97
	v_fma_f32 v220, v132, v152, v97
	v_fma_f32 v225, v132, v157, v97
	v_fma_f32 v226, v132, v158, v97
	v_fma_f32 v227, v132, v159, v97
	v_fma_f32 v228, v132, v160, v97
	v_fma_f32 v229, v132, v161, v97
	v_fma_f32 v230, v132, v162, v97
	v_fma_f32 v231, v132, v163, v97
	v_fma_f32 v232, v132, v164, v97
	v_fma_f32 v233, v132, v165, v97
	v_fma_f32 v234, v132, v166, v97
	v_fma_f32 v235, v132, v167, v97
	v_fma_f32 v236, v132, v168, v97
	v_fma_f32 v237, v132, v169, v97
	v_fma_f32 v238, v132, v170, v97
	v_fma_f32 v239, v132, v171, v97
	v_fma_f32 v240, v132, v172, v97
	v_fma_f32 v241, v132, v173, v97
	v_fma_f32 v242, v132, v174, v97
	v_fma_f32 v243, v132, v175, v97
	v_fma_f32 v244, v132, v178, v97
	v_fma_f32 v245, v132, v179, v97
	v_fma_f32 v246, v132, v180, v97
	v_fma_f32 v247, v132, v181, v97
	v_fma_f32 v248, v132, v182, v97
	v_fma_f32 v249, v132, v183, v97
	v_fma_f32 v250, v132, v184, v97
	v_fma_f32 v251, v132, v185, v97
	v_fma_f32 v252, v132, v186, v97
	v_fma_f32 v253, v132, v187, v97
	v_fmac_f32_e32 v97, v132, v188
	v_fmac_f32_e32 v194, v131, v74
	v_fmac_f32_e32 v195, v131, v89
	v_fmac_f32_e32 v196, v131, v91
	v_fmac_f32_e32 v197, v131, v93
	v_fmac_f32_e32 v198, v131, v135
	v_fmac_f32_e32 v202, v131, v136
	v_fmac_f32_e32 v203, v131, v137
	v_fmac_f32_e32 v204, v131, v138
	v_fmac_f32_e32 v205, v131, v139
	v_fmac_f32_e32 v207, v131, v141
	v_fmac_f32_e32 v208, v131, v142
	v_fmac_f32_e32 v209, v131, v143
	v_fmac_f32_e32 v210, v131, v144
	v_fmac_f32_e32 v211, v131, v145
	v_fmac_f32_e32 v212, v131, v146
	v_fmac_f32_e32 v213, v131, v147
	v_fmac_f32_e32 v214, v131, v148
	v_fmac_f32_e32 v215, v131, v149
	v_fmac_f32_e32 v217, v131, v150
	v_fmac_f32_e32 v218, v131, v151
	v_fmac_f32_e32 v219, v131, v152
	v_fmac_f32_e32 v220, v131, v153
	v_fmac_f32_e32 v221, v131, v154
	v_fmac_f32_e32 v222, v131, v155
	v_fmac_f32_e32 v223, v131, v156
	v_fmac_f32_e32 v224, v131, v157
	v_fmac_f32_e32 v225, v131, v158
	v_fmac_f32_e32 v226, v131, v159
	v_fmac_f32_e32 v227, v131, v160
	v_fmac_f32_e32 v228, v131, v161
	v_fmac_f32_e32 v229, v131, v162
	v_fmac_f32_e32 v230, v131, v163
	v_fmac_f32_e32 v231, v131, v164
	v_fmac_f32_e32 v232, v131, v165
	v_fmac_f32_e32 v233, v131, v166
	v_fmac_f32_e32 v234, v131, v167
	v_fmac_f32_e32 v235, v131, v168
	v_fmac_f32_e32 v236, v131, v169
	v_fmac_f32_e32 v237, v131, v170
	v_fmac_f32_e32 v238, v131, v171
	v_fmac_f32_e32 v239, v131, v172
	v_fmac_f32_e32 v240, v131, v173
	v_fmac_f32_e32 v241, v131, v174
	v_fmac_f32_e32 v242, v131, v175
	v_fmac_f32_e32 v243, v131, v178
	v_fmac_f32_e32 v244, v131, v179
	v_fmac_f32_e32 v245, v131, v180
	v_fmac_f32_e32 v246, v131, v181
	v_fmac_f32_e32 v247, v131, v182
	v_fmac_f32_e32 v248, v131, v183
	v_fmac_f32_e32 v249, v131, v184
	v_fmac_f32_e32 v250, v131, v185
	v_fmac_f32_e32 v251, v131, v186
	v_fmac_f32_e32 v252, v131, v187
	v_fmac_f32_e32 v253, v131, v188
	v_fmac_f32_e32 v97, v131, v189
	v_fmac_f32_e32 v193, v130, v74
	v_fmac_f32_e32 v194, v130, v89
	v_fmac_f32_e32 v195, v130, v91
	v_fmac_f32_e32 v196, v130, v93
	v_fmac_f32_e32 v197, v130, v135
	v_fmac_f32_e32 v198, v130, v136
	v_fmac_f32_e32 v202, v130, v137
	v_fmac_f32_e32 v203, v130, v138
	v_fmac_f32_e32 v204, v130, v139
	v_fmac_f32_e32 v205, v130, v140
	v_fmac_f32_e32 v206, v130, v141
	v_fmac_f32_e32 v207, v130, v142
	v_fmac_f32_e32 v208, v130, v143
	v_fmac_f32_e32 v209, v130, v144
	v_fmac_f32_e32 v210, v130, v145
	v_fmac_f32_e32 v211, v130, v146
	v_fmac_f32_e32 v212, v130, v147
	v_fmac_f32_e32 v213, v130, v148
	v_fmac_f32_e32 v214, v130, v149
	v_fmac_f32_e32 v215, v130, v150
	v_fmac_f32_e32 v217, v130, v151
	v_fmac_f32_e32 v218, v130, v152
	v_fmac_f32_e32 v219, v130, v153
	v_fmac_f32_e32 v220, v130, v154
	v_fmac_f32_e32 v221, v130, v155
	v_fmac_f32_e32 v222, v130, v156
	v_fmac_f32_e32 v223, v130, v157
	v_fmac_f32_e32 v224, v130, v158
	v_fmac_f32_e32 v225, v130, v159
	v_fmac_f32_e32 v226, v130, v160
	v_fmac_f32_e32 v227, v130, v161
	v_fmac_f32_e32 v228, v130, v162
	v_fmac_f32_e32 v229, v130, v163
	v_fmac_f32_e32 v230, v130, v164
	v_fmac_f32_e32 v231, v130, v165
	v_fmac_f32_e32 v232, v130, v166
	v_fmac_f32_e32 v233, v130, v167
	v_fmac_f32_e32 v234, v130, v168
	v_fmac_f32_e32 v235, v130, v169
	v_fmac_f32_e32 v236, v130, v170
	v_fmac_f32_e32 v237, v130, v171
	v_fmac_f32_e32 v238, v130, v172
	v_fmac_f32_e32 v239, v130, v173
	v_fmac_f32_e32 v240, v130, v174
	v_fmac_f32_e32 v241, v130, v175
	v_fmac_f32_e32 v242, v130, v178
	v_fmac_f32_e32 v243, v130, v179
	v_fmac_f32_e32 v244, v130, v180
	v_fmac_f32_e32 v245, v130, v181
	v_fmac_f32_e32 v246, v130, v182
	v_fmac_f32_e32 v247, v130, v183
	v_fmac_f32_e32 v248, v130, v184
	v_fmac_f32_e32 v249, v130, v185
	v_fmac_f32_e32 v250, v130, v186
	v_fmac_f32_e32 v251, v130, v187
	v_fmac_f32_e32 v252, v130, v188
	v_fmac_f32_e32 v253, v130, v189
	v_fmac_f32_e32 v97, v130, v190
	v_fmac_f32_e32 v133, v129, v67
	v_fmac_f32_e32 v192, v129, v74
	v_fmac_f32_e32 v193, v129, v89
	v_fmac_f32_e32 v194, v129, v91
	v_fmac_f32_e32 v195, v129, v93
	v_fmac_f32_e32 v196, v129, v135
	v_fmac_f32_e32 v197, v129, v136
	v_fmac_f32_e32 v198, v129, v137
	v_fmac_f32_e32 v202, v129, v138
	v_fmac_f32_e32 v203, v129, v139
	v_fmac_f32_e32 v204, v129, v140
	v_fmac_f32_e32 v205, v129, v141
	v_fmac_f32_e32 v206, v129, v142
	v_fmac_f32_e32 v207, v129, v143
	v_fmac_f32_e32 v208, v129, v144
	v_fmac_f32_e32 v209, v129, v145
	v_fmac_f32_e32 v210, v129, v146
	v_fmac_f32_e32 v211, v129, v147
	v_fmac_f32_e32 v212, v129, v148
	v_fmac_f32_e32 v213, v129, v149
	v_fmac_f32_e32 v214, v129, v150
	v_fmac_f32_e32 v215, v129, v151
	v_fmac_f32_e32 v217, v129, v152
	v_fmac_f32_e32 v218, v129, v153
	v_fmac_f32_e32 v219, v129, v154
	v_fmac_f32_e32 v220, v129, v155
	v_fmac_f32_e32 v221, v129, v156
	v_fmac_f32_e32 v222, v129, v157
	v_fmac_f32_e32 v223, v129, v158
	v_fmac_f32_e32 v224, v129, v159
	v_fmac_f32_e32 v225, v129, v160
	v_fmac_f32_e32 v226, v129, v161
	v_fmac_f32_e32 v227, v129, v162
	v_fmac_f32_e32 v228, v129, v163
	v_fmac_f32_e32 v229, v129, v164
	v_fmac_f32_e32 v230, v129, v165
	v_fmac_f32_e32 v231, v129, v166
	v_fmac_f32_e32 v232, v129, v167
	v_fmac_f32_e32 v233, v129, v168
	v_fmac_f32_e32 v234, v129, v169
	v_fmac_f32_e32 v235, v129, v170
	v_fmac_f32_e32 v236, v129, v171
	v_fmac_f32_e32 v237, v129, v172
	v_fmac_f32_e32 v238, v129, v173
	v_fmac_f32_e32 v239, v129, v174
	v_fmac_f32_e32 v240, v129, v175
	v_fmac_f32_e32 v241, v129, v178
	v_fmac_f32_e32 v242, v129, v179
	v_fmac_f32_e32 v243, v129, v180
	v_fmac_f32_e32 v244, v129, v181
	v_fmac_f32_e32 v245, v129, v182
	v_fmac_f32_e32 v246, v129, v183
	v_fmac_f32_e32 v247, v129, v184
	v_fmac_f32_e32 v248, v129, v185
	v_fmac_f32_e32 v249, v129, v186
	v_fmac_f32_e32 v250, v129, v187
	v_fmac_f32_e32 v251, v129, v188
	v_fmac_f32_e32 v252, v129, v189
	v_fmac_f32_e32 v253, v129, v190
	v_fmac_f32_e32 v97, v129, v191
	s_waitcnt vmcnt(0)
	v_cvt_pk_bf16_f32 v63, v66, v63
	global_load_dword v74, v[100:101], off offset:1024
	global_load_dword v89, v[100:101], off offset:1088
	global_load_dword v91, v[100:101], off offset:1152
	global_load_dword v93, v[100:101], off offset:1216
	global_load_dword v129, v[70:71], off offset:1024
	global_load_dword v130, v[70:71], off offset:1088
	global_load_dword v131, v[70:71], off offset:1152
	global_load_dword v132, v[70:71], off offset:1216
	global_load_dword v66, v[64:65], off offset:1024
	global_load_dword v67, v[64:65], off offset:1088
	global_load_dword v68, v[64:65], off offset:1152
	s_nop 0
	global_load_dword v64, v[64:65], off offset:1216
	v_cvt_pk_bf16_f32 v65, v199, v199
	ds_write_b16 v73, v65
	v_cvt_pk_bf16_f32 v65, v200, v200
	ds_write_b16 v73, v65 offset:144
	v_cvt_pk_bf16_f32 v65, v201, v201
	ds_write_b16 v73, v65 offset:288
	v_cvt_pk_bf16_f32 v65, v133, v133
	ds_write_b16 v73, v65 offset:432
	v_cvt_pk_bf16_f32 v65, v134, v134
	ds_write_b16 v73, v65 offset:576
	v_cvt_pk_bf16_f32 v65, v192, v192
	ds_write_b16 v73, v65 offset:720
	v_cvt_pk_bf16_f32 v65, v193, v193
	ds_write_b16 v73, v65 offset:864
	v_cvt_pk_bf16_f32 v65, v194, v194
	ds_write_b16 v73, v65 offset:1008
	v_cvt_pk_bf16_f32 v65, v195, v195
	ds_write_b16 v73, v65 offset:1152
	v_cvt_pk_bf16_f32 v65, v196, v196
	ds_write_b16 v73, v65 offset:1296
	v_cvt_pk_bf16_f32 v65, v197, v197
	ds_write_b16 v73, v65 offset:1440
	v_cvt_pk_bf16_f32 v65, v198, v198
	ds_write_b16 v73, v65 offset:1584
	v_cvt_pk_bf16_f32 v65, v202, v202
	ds_write_b16 v73, v65 offset:1728
	v_cvt_pk_bf16_f32 v65, v203, v203
	ds_write_b16 v73, v65 offset:1872
	v_cvt_pk_bf16_f32 v65, v204, v204
	ds_write_b16 v73, v65 offset:2016
	v_cvt_pk_bf16_f32 v65, v205, v205
	ds_write_b16 v73, v65 offset:2160
	v_cvt_pk_bf16_f32 v65, v206, v206
	ds_write_b16 v73, v65 offset:2304
	v_cvt_pk_bf16_f32 v65, v207, v207
	ds_write_b16 v73, v65 offset:2448
	v_cvt_pk_bf16_f32 v65, v208, v208
	ds_write_b16 v73, v65 offset:2592
	v_cvt_pk_bf16_f32 v65, v209, v209
	ds_write_b16 v73, v65 offset:2736
	v_cvt_pk_bf16_f32 v65, v210, v210
	ds_write_b16 v73, v65 offset:2880
	v_cvt_pk_bf16_f32 v65, v211, v211
	ds_write_b16 v73, v65 offset:3024
	v_cvt_pk_bf16_f32 v65, v212, v212
	ds_write_b16 v73, v65 offset:3168
	v_cvt_pk_bf16_f32 v65, v213, v213
	ds_write_b16 v73, v65 offset:3312
	v_cvt_pk_bf16_f32 v65, v214, v214
	ds_write_b16 v73, v65 offset:3456
	v_cvt_pk_bf16_f32 v65, v215, v215
	ds_write_b16 v73, v65 offset:3600
	v_cvt_pk_bf16_f32 v65, v217, v217
	ds_write_b16 v73, v65 offset:3744
	v_cvt_pk_bf16_f32 v65, v218, v218
	ds_write_b16 v73, v65 offset:3888
	v_cvt_pk_bf16_f32 v65, v219, v219
	ds_write_b16 v73, v65 offset:4032
	v_cvt_pk_bf16_f32 v65, v220, v220
	ds_write_b16 v73, v65 offset:4176
	v_cvt_pk_bf16_f32 v65, v221, v221
	ds_write_b16 v73, v65 offset:4320
	v_cvt_pk_bf16_f32 v65, v222, v222
	ds_write_b16 v73, v65 offset:4464
	v_cvt_pk_bf16_f32 v65, v223, v223
	ds_write_b16 v73, v65 offset:4608
	v_cvt_pk_bf16_f32 v65, v224, v224
	ds_write_b16 v73, v65 offset:4752
	v_cvt_pk_bf16_f32 v65, v225, v225
	ds_write_b16 v73, v65 offset:4896
	v_cvt_pk_bf16_f32 v65, v226, v226
	ds_write_b16 v73, v65 offset:5040
	v_cvt_pk_bf16_f32 v65, v227, v227
	ds_write_b16 v73, v65 offset:5184
	v_cvt_pk_bf16_f32 v65, v228, v228
	ds_write_b16 v73, v65 offset:5328
	v_cvt_pk_bf16_f32 v65, v229, v229
	ds_write_b16 v73, v65 offset:5472
	v_cvt_pk_bf16_f32 v65, v230, v230
	ds_write_b16 v73, v65 offset:5616
	v_cvt_pk_bf16_f32 v65, v231, v231
	ds_write_b16 v73, v65 offset:5760
	v_cvt_pk_bf16_f32 v65, v232, v232
	ds_write_b16 v73, v65 offset:5904
	v_cvt_pk_bf16_f32 v65, v233, v233
	ds_write_b16 v73, v65 offset:6048
	v_cvt_pk_bf16_f32 v65, v234, v234
	ds_write_b16 v73, v65 offset:6192
	v_cvt_pk_bf16_f32 v65, v235, v235
	ds_write_b16 v73, v65 offset:6336
	v_cvt_pk_bf16_f32 v65, v236, v236
	ds_write_b16 v73, v65 offset:6480
	v_cvt_pk_bf16_f32 v65, v237, v237
	ds_write_b16 v73, v65 offset:6624
	v_cvt_pk_bf16_f32 v65, v238, v238
	ds_write_b16 v73, v65 offset:6768
	v_cvt_pk_bf16_f32 v65, v239, v239
	ds_write_b16 v73, v65 offset:6912
	v_cvt_pk_bf16_f32 v65, v240, v240
	ds_write_b16 v73, v65 offset:7056
	v_cvt_pk_bf16_f32 v65, v241, v241
	ds_write_b16 v73, v65 offset:7200
	v_cvt_pk_bf16_f32 v65, v242, v242
	ds_write_b16 v73, v65 offset:7344
	v_cvt_pk_bf16_f32 v65, v243, v243
	ds_write_b16 v73, v65 offset:7488
	v_cvt_pk_bf16_f32 v65, v244, v244
	ds_write_b16 v73, v65 offset:7632
	v_cvt_pk_bf16_f32 v65, v245, v245
	ds_write_b16 v73, v65 offset:7776
	v_cvt_pk_bf16_f32 v65, v246, v246
	ds_write_b16 v73, v65 offset:7920
	v_cvt_pk_bf16_f32 v65, v247, v247
	ds_write_b16 v73, v65 offset:8064
	v_cvt_pk_bf16_f32 v65, v248, v248
	ds_write_b16 v73, v65 offset:8208
	v_cvt_pk_bf16_f32 v65, v249, v249
	ds_write_b16 v73, v65 offset:8352
	v_cvt_pk_bf16_f32 v65, v250, v250
	ds_write_b16 v73, v65 offset:8496
	v_cvt_pk_bf16_f32 v65, v251, v251
	ds_write_b16 v73, v65 offset:8640
	v_cvt_pk_bf16_f32 v65, v252, v252
	ds_write_b16 v73, v65 offset:8784
	v_cvt_pk_bf16_f32 v65, v253, v253
	ds_write_b16 v73, v65 offset:8928
	v_cvt_pk_bf16_f32 v65, v97, v97
	ds_write_b16 v73, v65 offset:9072
	s_waitcnt vmcnt(3)
	v_mul_f32_e32 v65, 0xbfb8aa3b, v66
	v_exp_f32_e32 v97, v65
	s_waitcnt vmcnt(2)
	v_mul_f32_e32 v66, 0xbfb8aa3b, v67
	v_exp_f32_e32 v100, v66
	s_waitcnt vmcnt(1)
	v_mul_f32_e32 v67, 0xbfb8aa3b, v68
	s_waitcnt vmcnt(0)
	v_mul_f32_e32 v64, 0xbfb8aa3b, v64
	v_exp_f32_e32 v101, v67
	v_add_f32_e32 v134, 1.0, v97
	v_exp_f32_e32 v133, v64
	v_frexp_mant_f32_e32 v139, v134
	v_cvt_f64_f32_e32 v[64:65], v134
	v_add_f32_e32 v135, 1.0, v100
	v_frexp_exp_i32_f64_e32 v64, v[64:65]
	v_cmp_gt_f32_e32 vcc, s88, v139
	v_frexp_mant_f32_e32 v141, v135
	v_cvt_f64_f32_e32 v[66:67], v135
	v_subbrev_co_u32_e32 v64, vcc, 0, v64, vcc
	v_add_f32_e32 v136, 1.0, v101
	v_frexp_exp_i32_f64_e32 v66, v[66:67]
	v_cmp_gt_f32_e32 vcc, s88, v141
	v_frexp_mant_f32_e32 v143, v136
	v_cvt_f64_f32_e32 v[68:69], v136
	v_subbrev_co_u32_e32 v66, vcc, 0, v66, vcc
	v_add_f32_e32 v137, 1.0, v133
	v_add_f32_e32 v138, -1.0, v134
	v_frexp_exp_i32_f64_e32 v68, v[68:69]
	v_cmp_gt_f32_e32 vcc, s88, v143
	v_add_f32_e32 v140, -1.0, v135
	v_frexp_mant_f32_e32 v145, v137
	v_cvt_f64_f32_e32 v[70:71], v137
	v_sub_f32_e32 v146, v138, v134
	v_subbrev_co_u32_e32 v68, vcc, 0, v68, vcc
	v_add_f32_e32 v142, -1.0, v136
	v_add_f32_e32 v144, -1.0, v137
	v_sub_f32_e32 v138, v97, v138
	v_sub_f32_e32 v65, v140, v135
	v_frexp_exp_i32_f64_e32 v70, v[70:71]
	v_add_f32_e32 v71, 1.0, v146
	v_cmp_gt_f32_e32 vcc, s88, v145
	v_sub_f32_e32 v140, v100, v140
	v_sub_f32_e32 v67, v142, v136
	v_sub_f32_e32 v69, v144, v137
	v_add_f32_e32 v65, 1.0, v65
	v_subbrev_co_u32_e32 v70, vcc, 0, v70, vcc
	v_add_f32_e32 v71, v138, v71
	v_sub_u32_e32 v138, 0, v64
	v_sub_f32_e32 v142, v101, v142
	v_sub_f32_e32 v144, v133, v144
	v_add_f32_e32 v67, 1.0, v67
	v_add_f32_e32 v69, 1.0, v69
	v_add_f32_e32 v65, v140, v65
	v_sub_u32_e32 v139, 0, v66
	v_sub_u32_e32 v140, 0, v68
	v_sub_u32_e32 v141, 0, v70
	v_cvt_f32_i32_e32 v70, v70
	v_ldexp_f32 v134, v134, v138
	v_cvt_f32_i32_e32 v64, v64
	v_add_f32_e32 v67, v142, v67
	v_add_f32_e32 v69, v144, v69
	v_ldexp_f32 v71, v71, v138
	v_ldexp_f32 v135, v135, v139
	v_ldexp_f32 v65, v65, v139
	v_ldexp_f32 v136, v136, v140
	v_ldexp_f32 v137, v137, v141
	v_add_f32_e32 v138, -1.0, v134
	v_add_f32_e32 v139, 1.0, v134
	v_cvt_f32_i32_e32 v66, v66
	v_cvt_f32_i32_e32 v68, v68
	v_ldexp_f32 v67, v67, v140
	v_ldexp_f32 v69, v69, v141
	v_add_f32_e32 v140, -1.0, v135
	v_add_f32_e32 v141, 1.0, v135
	v_add_f32_e32 v142, -1.0, v136
	v_add_f32_e32 v143, 1.0, v136
	v_add_f32_e32 v144, -1.0, v137
	v_add_f32_e32 v145, 1.0, v137
	v_add_f32_e32 v146, 1.0, v138
	v_add_f32_e32 v147, -1.0, v139
	v_add_f32_e32 v148, 1.0, v140
	v_add_f32_e32 v149, -1.0, v141
	v_add_f32_e32 v150, 1.0, v142
	v_add_f32_e32 v151, -1.0, v143
	v_add_f32_e32 v152, 1.0, v144
	v_add_f32_e32 v153, -1.0, v145
	v_sub_f32_e32 v146, v134, v146
	v_sub_f32_e32 v134, v134, v147
	v_sub_f32_e32 v148, v135, v148
	v_sub_f32_e32 v135, v135, v149
	v_sub_f32_e32 v150, v136, v150
	v_sub_f32_e32 v136, v136, v151
	v_sub_f32_e32 v152, v137, v152
	v_sub_f32_e32 v137, v137, v153
	v_mul_f32_e32 v153, 0x3f317218, v70
	v_add_f32_e32 v146, v71, v146
	v_add_f32_e32 v71, v71, v134
	v_mul_f32_e32 v147, 0x3f317218, v64
	v_add_f32_e32 v148, v65, v148
	v_add_f32_e32 v65, v65, v135
	v_add_f32_e32 v150, v67, v150
	v_add_f32_e32 v67, v67, v136
	v_add_f32_e32 v152, v69, v152
	v_add_f32_e32 v69, v69, v137
	v_fma_f32 v137, v70, s89, -v153
	v_add_f32_e32 v154, v138, v146
	v_add_f32_e32 v155, v139, v71
	v_mul_f32_e32 v149, 0x3f317218, v66
	v_mul_f32_e32 v151, 0x3f317218, v68
	v_fma_f32 v134, v64, s89, -v147
	v_add_f32_e32 v156, v141, v65
	v_add_f32_e32 v157, v143, v67
	v_fmac_f32_e32 v137, 0xb102e308, v70
	v_sub_f32_e32 v70, v154, v138
	v_sub_f32_e32 v138, v155, v139
	v_rcp_f32_e32 v139, v155
	v_fma_f32 v135, v66, s89, -v149
	v_fma_f32 v136, v68, s89, -v151
	v_fmac_f32_e32 v134, 0xb102e308, v64
	v_add_f32_e32 v158, v145, v69
	v_rcp_f32_e32 v160, v156
	v_rcp_f32_e32 v162, v157
	v_fmac_f32_e32 v135, 0xb102e308, v66
	v_fmac_f32_e32 v136, 0xb102e308, v68
	v_add_f32_e32 v159, v147, v134
	v_rcp_f32_e32 v164, v158
	v_sub_f32_e32 v141, v156, v141
	v_add_f32_e32 v161, v149, v135
	v_sub_f32_e32 v143, v157, v143
	v_add_f32_e32 v163, v151, v136
	v_sub_f32_e32 v71, v71, v138
	v_sub_f32_e32 v138, v159, v147
	v_add_f32_e32 v64, v140, v148
	v_add_f32_e32 v66, v142, v150
	v_sub_f32_e32 v145, v158, v145
	v_add_f32_e32 v165, v153, v137
	v_sub_f32_e32 v65, v65, v141
	v_sub_f32_e32 v141, v161, v149
	v_sub_f32_e32 v67, v67, v143
	v_sub_f32_e32 v143, v163, v151
	v_sub_f32_e32 v134, v134, v138
	v_mul_f32_e32 v138, v154, v139
	v_add_f32_e32 v68, v144, v152
	v_sub_f32_e32 v140, v64, v140
	v_sub_f32_e32 v142, v66, v142
	v_sub_f32_e32 v70, v146, v70
	v_sub_f32_e32 v69, v69, v145
	v_sub_f32_e32 v145, v165, v153
	v_sub_f32_e32 v135, v135, v141
	v_sub_f32_e32 v136, v136, v143
	v_mul_f32_e32 v141, v64, v160
	v_mul_f32_e32 v143, v66, v162
	v_mul_f32_e32 v146, v155, v138
	v_sub_f32_e32 v144, v68, v144
	v_sub_f32_e32 v140, v148, v140
	v_sub_f32_e32 v142, v150, v142
	v_sub_f32_e32 v137, v137, v145
	v_mul_f32_e32 v145, v68, v164
	v_mul_f32_e32 v147, v156, v141
	v_mul_f32_e32 v148, v157, v143
	v_fma_f32 v150, v138, v155, -v146
	v_sub_f32_e32 v144, v152, v144
	v_mul_f32_e32 v149, v158, v145
	v_fma_f32 v151, v141, v156, -v147
	v_fma_f32 v152, v143, v157, -v148
	v_fmac_f32_e32 v150, v138, v71
	v_fma_f32 v153, v145, v158, -v149
	v_fmac_f32_e32 v151, v141, v65
	v_fmac_f32_e32 v152, v143, v67
	v_add_f32_e32 v166, v146, v150
	v_fmac_f32_e32 v153, v145, v69
	v_add_f32_e32 v167, v147, v151
	v_add_f32_e32 v168, v148, v152
	v_sub_f32_e32 v170, v154, v166
	v_add_f32_e32 v169, v149, v153
	v_sub_f32_e32 v146, v166, v146
	v_sub_f32_e32 v171, v64, v167
	v_sub_f32_e32 v172, v66, v168
	v_sub_f32_e32 v154, v154, v170
	v_sub_f32_e32 v173, v68, v169
	v_sub_f32_e32 v146, v146, v150
	v_sub_f32_e32 v64, v64, v171
	v_sub_f32_e32 v66, v66, v172
	v_sub_f32_e32 v150, v154, v166
	v_sub_f32_e32 v147, v167, v147
	v_sub_f32_e32 v148, v168, v148
	v_sub_f32_e32 v68, v68, v173
	v_sub_f32_e32 v64, v64, v167
	v_sub_f32_e32 v66, v66, v168
	v_add_f32_e32 v70, v70, v150
	v_sub_f32_e32 v149, v169, v149
	v_sub_f32_e32 v147, v147, v151
	v_sub_f32_e32 v148, v148, v152
	v_sub_f32_e32 v68, v68, v169
	v_add_f32_e32 v64, v140, v64
	v_add_f32_e32 v66, v142, v66
	v_add_f32_e32 v70, v146, v70
	v_sub_f32_e32 v149, v149, v153
	v_add_f32_e32 v68, v144, v68
	v_add_f32_e32 v64, v147, v64
	v_add_f32_e32 v66, v148, v66
	v_add_f32_e32 v140, v170, v70
	v_add_f32_e32 v68, v149, v68
	v_add_f32_e32 v142, v171, v64
	v_add_f32_e32 v144, v172, v66
	v_mul_f32_e32 v147, v139, v140
	v_add_f32_e32 v146, v173, v68
	v_sub_f32_e32 v148, v170, v140
	v_mul_f32_e32 v149, v160, v142
	v_mul_f32_e32 v151, v162, v144
	v_mul_f32_e32 v166, v155, v147
	v_sub_f32_e32 v150, v171, v142
	v_sub_f32_e32 v152, v172, v144
	v_mul_f32_e32 v153, v164, v146
	v_add_f32_e32 v70, v70, v148
	v_add_f32_e32 v148, v138, v147
	v_mul_f32_e32 v167, v156, v149
	v_mul_f32_e32 v168, v157, v151
	v_fma_f32 v155, v147, v155, -v166
	v_sub_f32_e32 v154, v173, v146
	v_add_f32_e32 v64, v64, v150
	v_add_f32_e32 v150, v141, v149
	v_add_f32_e32 v66, v66, v152
	v_add_f32_e32 v152, v143, v151
	v_mul_f32_e32 v169, v158, v153
	v_sub_f32_e32 v138, v148, v138
	v_fma_f32 v156, v149, v156, -v167
	v_fma_f32 v157, v151, v157, -v168
	v_fmac_f32_e32 v155, v147, v71
	v_add_f32_e32 v68, v68, v154
	v_add_f32_e32 v154, v145, v153
	v_sub_f32_e32 v141, v150, v141
	v_sub_f32_e32 v143, v152, v143
	v_fma_f32 v158, v153, v158, -v169
	v_sub_f32_e32 v71, v147, v138
	v_fmac_f32_e32 v156, v149, v65
	v_fmac_f32_e32 v157, v151, v67
	v_add_f32_e32 v138, v166, v155
	v_sub_f32_e32 v145, v154, v145
	v_sub_f32_e32 v65, v149, v141
	v_sub_f32_e32 v67, v151, v143
	v_fmac_f32_e32 v158, v153, v69
	v_add_f32_e32 v141, v167, v156
	v_add_f32_e32 v143, v168, v157
	v_sub_f32_e32 v149, v140, v138
	v_sub_f32_e32 v69, v153, v145
	v_add_f32_e32 v145, v169, v158
	v_sub_f32_e32 v151, v141, v167
	v_sub_f32_e32 v153, v142, v141
	v_sub_f32_e32 v167, v144, v143
	v_sub_f32_e32 v140, v140, v149
	v_sub_f32_e32 v147, v138, v166
	v_sub_f32_e32 v166, v143, v168
	v_sub_f32_e32 v168, v145, v169
	v_sub_f32_e32 v169, v146, v145
	v_sub_f32_e32 v142, v142, v153
	v_sub_f32_e32 v144, v144, v167
	v_sub_f32_e32 v138, v140, v138
	v_sub_f32_e32 v147, v147, v155
	v_sub_f32_e32 v146, v146, v169
	v_sub_f32_e32 v140, v142, v141
	v_sub_f32_e32 v141, v144, v143
	v_add_f32_e32 v70, v70, v138
	v_sub_f32_e32 v151, v151, v156
	v_sub_f32_e32 v155, v166, v157
	v_sub_f32_e32 v142, v146, v145
	v_add_f32_e32 v64, v64, v140
	v_add_f32_e32 v66, v66, v141
	v_add_f32_e32 v70, v147, v70
	v_sub_f32_e32 v156, v168, v158
	v_add_f32_e32 v68, v68, v142
	v_add_f32_e32 v64, v151, v64
	v_add_f32_e32 v66, v155, v66
	v_add_f32_e32 v70, v149, v70
	v_add_f32_e32 v68, v156, v68
	v_add_f32_e32 v64, v153, v64
	v_add_f32_e32 v66, v167, v66
	v_mul_f32_e32 v70, v139, v70
	v_add_f32_e32 v68, v169, v68
	v_mul_f32_e32 v64, v160, v64
	v_mul_f32_e32 v66, v162, v66
	v_add_f32_e32 v70, v71, v70
	v_mul_f32_e32 v68, v164, v68
	v_add_f32_e32 v64, v65, v64
	v_add_f32_e32 v65, v67, v66
	v_add_f32_e32 v67, v148, v70
	v_add_f32_e32 v66, v69, v68
	v_add_f32_e32 v68, v150, v64
	v_mul_f32_e32 v138, v67, v67
	v_add_f32_e32 v69, v152, v65
	v_sub_f32_e32 v139, v67, v148
	v_mul_f32_e32 v141, v68, v68
	v_sub_f32_e32 v142, v68, v150
	v_fmamk_f32 v150, v138, 0x3e9b6dac, v123
	v_add_f32_e32 v71, v154, v66
	v_ldexp_f32 v140, v67, 1
	v_mul_f32_e32 v144, v69, v69
	v_sub_f32_e32 v70, v70, v139
	v_mul_f32_e32 v67, v67, v138
	v_fmamk_f32 v139, v141, 0x3e9b6dac, v123
	v_fmaak_f32 v138, v138, v150, 0x3f2aaada
	v_ldexp_f32 v143, v68, 1
	v_sub_f32_e32 v145, v69, v152
	v_mul_f32_e32 v147, v71, v71
	v_sub_f32_e32 v64, v64, v142
	v_mul_f32_e32 v68, v68, v141
	v_fmamk_f32 v142, v144, 0x3e9b6dac, v123
	v_fmaak_f32 v139, v141, v139, 0x3f2aaada
	v_mul_f32_e32 v67, v67, v138
	v_ldexp_f32 v146, v69, 1
	v_sub_f32_e32 v65, v65, v145
	v_mul_f32_e32 v69, v69, v144
	v_fmamk_f32 v145, v147, 0x3e9b6dac, v123
	v_fmaak_f32 v141, v144, v142, 0x3f2aaada
	v_mul_f32_e32 v68, v68, v139
	v_add_f32_e32 v138, v140, v67
	v_sub_f32_e32 v148, v71, v154
	v_ldexp_f32 v149, v71, 1
	v_mul_f32_e32 v71, v71, v147
	v_fmaak_f32 v142, v147, v145, 0x3f2aaada
	v_mul_f32_e32 v69, v69, v141
	v_add_f32_e32 v139, v143, v68
	v_sub_f32_e32 v140, v138, v140
	v_ldexp_f32 v70, v70, 1
	v_mul_f32_e32 v71, v71, v142
	v_add_f32_e32 v141, v146, v69
	v_sub_f32_e32 v143, v139, v143
	v_sub_f32_e32 v67, v67, v140
	v_ldexp_f32 v64, v64, 1
	v_add_f32_e32 v142, v149, v71
	v_sub_f32_e32 v144, v141, v146
	v_sub_f32_e32 v68, v68, v143
	v_add_f32_e32 v67, v70, v67
	v_sub_f32_e32 v66, v66, v148
	v_ldexp_f32 v65, v65, 1
	v_sub_f32_e32 v145, v142, v149
	v_sub_f32_e32 v69, v69, v144
	v_add_f32_e32 v64, v64, v68
	v_add_f32_e32 v68, v138, v67
	v_ldexp_f32 v66, v66, 1
	v_sub_f32_e32 v71, v71, v145
	v_add_f32_e32 v65, v65, v69
	v_add_f32_e32 v69, v139, v64
	v_sub_f32_e32 v138, v68, v138
	v_add_f32_e32 v140, v159, v68
	v_add_f32_e32 v66, v66, v71
	v_add_f32_e32 v70, v141, v65
	v_sub_f32_e32 v139, v69, v139
	v_add_f32_e32 v143, v161, v69
	v_sub_f32_e32 v67, v67, v138
	v_sub_f32_e32 v138, v140, v159
	v_add_f32_e32 v71, v142, v66
	v_sub_f32_e32 v141, v70, v141
	v_add_f32_e32 v144, v163, v70
	v_sub_f32_e32 v64, v64, v139
	v_sub_f32_e32 v139, v143, v161
	v_sub_f32_e32 v146, v140, v138
	v_sub_f32_e32 v68, v68, v138
	v_add_f32_e32 v138, v134, v67
	v_sub_f32_e32 v142, v71, v142
	v_add_f32_e32 v145, v165, v71
	v_sub_f32_e32 v65, v65, v141
	v_sub_f32_e32 v141, v144, v163
	v_sub_f32_e32 v147, v143, v139
	v_sub_f32_e32 v69, v69, v139
	v_add_f32_e32 v139, v135, v64
	v_sub_f32_e32 v146, v159, v146
	v_sub_f32_e32 v150, v138, v134
	v_sub_f32_e32 v66, v66, v142
	v_sub_f32_e32 v142, v145, v165
	v_sub_f32_e32 v148, v144, v141
	v_sub_f32_e32 v70, v70, v141
	v_add_f32_e32 v141, v136, v65
	v_sub_f32_e32 v147, v161, v147
	v_sub_f32_e32 v151, v139, v135
	v_add_f32_e32 v68, v68, v146
	v_sub_f32_e32 v146, v138, v150
	v_sub_f32_e32 v149, v145, v142
	v_sub_f32_e32 v71, v71, v142
	v_add_f32_e32 v142, v137, v66
	v_sub_f32_e32 v148, v163, v148
	v_sub_f32_e32 v152, v141, v136
	v_sub_f32_e32 v67, v67, v150
	v_add_f32_e32 v69, v69, v147
	v_sub_f32_e32 v147, v139, v151
	v_sub_f32_e32 v134, v134, v146
	v_add_f32_e32 v68, v138, v68
	v_sub_f32_e32 v149, v165, v149
	v_sub_f32_e32 v153, v142, v137
	v_sub_f32_e32 v64, v64, v151
	v_add_f32_e32 v70, v70, v148
	v_sub_f32_e32 v148, v141, v152
	v_sub_f32_e32 v135, v135, v147
	v_add_f32_e32 v69, v139, v69
	v_add_f32_e32 v67, v67, v134
	v_add_f32_e32 v134, v140, v68
	v_sub_f32_e32 v65, v65, v152
	v_add_f32_e32 v71, v71, v149
	v_sub_f32_e32 v149, v142, v153
	v_sub_f32_e32 v136, v136, v148
	v_add_f32_e32 v70, v141, v70
	v_add_f32_e32 v64, v64, v135
	v_add_f32_e32 v135, v143, v69
	v_sub_f32_e32 v138, v134, v140
	v_sub_f32_e32 v66, v66, v153
	v_sub_f32_e32 v137, v137, v149
	v_add_f32_e32 v71, v142, v71
	v_add_f32_e32 v65, v65, v136
	v_add_f32_e32 v136, v144, v70
	v_sub_f32_e32 v139, v135, v143
	v_sub_f32_e32 v68, v68, v138
	v_add_f32_e32 v66, v66, v137
	v_add_f32_e32 v137, v145, v71
	v_sub_f32_e32 v140, v136, v144
	v_sub_f32_e32 v69, v69, v139
	v_add_f32_e32 v67, v67, v68
	v_sub_f32_e32 v141, v137, v145
	v_sub_f32_e32 v70, v70, v140
	v_add_f32_e32 v64, v64, v69
	v_add_f32_e32 v67, v134, v67
	v_cmp_neq_f32_e32 vcc, s90, v97
	v_sub_f32_e32 v71, v71, v141
	v_add_f32_e32 v65, v65, v70
	v_add_f32_e32 v64, v135, v64
	v_cndmask_b32_e32 v67, v126, v67, vcc
	v_cmp_neq_f32_e32 vcc, s90, v100
	v_add_f32_e32 v66, v66, v71
	v_add_f32_e32 v65, v136, v65
	v_cndmask_b32_e32 v64, v126, v64, vcc
	v_cmp_neq_f32_e32 vcc, s90, v101
	v_add_f32_e32 v66, v137, v66
	s_nop 0
	v_cndmask_b32_e32 v65, v126, v65, vcc
	v_cmp_neq_f32_e32 vcc, s90, v133
	s_nop 1
	v_cndmask_b32_e32 v66, v126, v66, vcc
	v_cmp_ngt_f32_e32 vcc, -1.0, v97
	s_nop 1
	v_cndmask_b32_e32 v67, v127, v67, vcc
	v_cmp_ngt_f32_e32 vcc, -1.0, v100
	s_nop 1
	v_cndmask_b32_e32 v64, v127, v64, vcc
	v_cmp_ngt_f32_e32 vcc, -1.0, v101
	s_nop 1
	v_cndmask_b32_e32 v65, v127, v65, vcc
	v_cmp_ngt_f32_e32 vcc, -1.0, v133
	s_nop 1
	v_cndmask_b32_e32 v66, v127, v66, vcc
	v_cmp_neq_f32_e32 vcc, -1.0, v97
	s_nop 1
	v_cndmask_b32_e32 v67, v128, v67, vcc
	v_cmp_neq_f32_e32 vcc, -1.0, v100
	s_nop 1
	v_cndmask_b32_e32 v64, v128, v64, vcc
	v_cmp_neq_f32_e32 vcc, -1.0, v101
	s_nop 1
	v_cndmask_b32_e32 v65, v128, v65, vcc
	v_cmp_neq_f32_e32 vcc, -1.0, v133
	s_nop 1
	v_cndmask_b32_e32 v66, v128, v66, vcc
	v_cmp_lt_f32_e64 vcc, |v97|, s91
	s_nop 1
	v_cndmask_b32_e32 v67, v67, v97, vcc
	v_cmp_lt_f32_e64 vcc, |v100|, s91
	v_mul_f32_e32 v97, 0xc1000000, v67
	s_nop 0
	v_cndmask_b32_e32 v64, v64, v100, vcc
	v_cmp_lt_f32_e64 vcc, |v101|, s91
	s_nop 1
	v_cndmask_b32_e32 v65, v65, v101, vcc
	v_cmp_lt_f32_e64 vcc, |v133|, s91
	v_mul_f32_e32 v134, 0xc1000000, v65
	v_mov_b32_e32 v101, 0
	v_cndmask_b32_e32 v66, v66, v133, vcc
	v_mul_f32_e32 v133, 0xc1000000, v64
	v_mul_f32_e32 v135, 0xc1000000, v66
